# nt cache hints on the fast attention units' read-once Q loads and O stores (keep the XCD L2 for the K/V tiles)
# baseline (speedup 1.0000x reference)
; __device__ __forceinline__ unsigned cvt_pk_bf16(float lo, float hi) { unsigned r; asm volatile("v_cvt_pk_bf16_f32 %0, %1, %2" : "=v"(r) : "v"(lo), "v"(hi)); return r; }
; __device__ __forceinline__ int crow(int r, int hi) { return (r & 3) + 8 * (r >> 2) + 4 * hi; }
;     ...
;         if (hib == 0) li2[r32b] = l_reg; asm volatile("s_waitcnt lgkmcnt(0)" ::: "memory");
;         __syncthreads();
;         bf16_t* stash = (bf16_t*)(lds + OFF_Q) + wid2 * 4096;
;         bf16_t* stg = (mode == 1) ? stash : ((bf16_t*)lds + wid2 * 4096);
; #pragma unroll
;         for (int r = 0; r < 16; ++r) { const int orow = crow(r, hib); const float rl = __builtin_amdgcn_rcpf(li2[orow]);
; #pragma unroll
;             for (int d0 = 0; d0 < 4; ++d0) { const float v = o[d0][r] * rl; stg[orow * 128 + d0 * 32 + r32b] = (bf16_t)(cvt_pk_bf16(v, v) & 0xffffu); } }
.LBB0_525:
	s_or_b64 exec, exec, s[0:1]
	v_lshrrev_b32_e32 v66, 3, v64
	v_and_b32_e32 v66, 4, v66
	v_lshl_add_u32 v68, v66, 2, v68
	s_waitcnt lgkmcnt(0)
	s_waitcnt lgkmcnt(0)
	s_barrier
	ds_read_b32 v69, v68
	v_ashrrev_i32_e32 v70, 6, v64
	v_lshl_add_u32 v71, v70, 13, 0
	v_lshlrev_b32_e32 v67, 1, v67
	v_lshlrev_b32_e32 v66, 8, v66
	s_waitcnt lgkmcnt(0)
	v_rcp_f32_e32 v69, v69
	v_add3_u32 v66, v71, v67, v66
	s_add_i32 s51, s51, s15
	s_cmpk_gt_i32 s51, 0x3ff
	v_mul_f32_e32 v0, v0, v69
	v_cvt_pk_bf16_f32 v0, v0, v0
	ds_write_b16 v66, v0
	v_mul_f32_e32 v0, v16, v69
	v_cvt_pk_bf16_f32 v0, v0, v0
	ds_write_b16 v66, v0 offset:64
	v_mul_f32_e32 v0, v32, v69
	v_cvt_pk_bf16_f32 v0, v0, v0
	ds_write_b16 v66, v0 offset:128
	v_mul_f32_e32 v0, v48, v69
	v_cvt_pk_bf16_f32 v0, v0, v0
	ds_read_b32 v16, v68 offset:4
	ds_write_b16 v66, v0 offset:192
	s_waitcnt lgkmcnt(1)
	v_rcp_f32_e32 v16, v16
	s_nop 0
	v_mul_f32_e32 v0, v1, v16
	v_cvt_pk_bf16_f32 v0, v0, v0
	ds_write_b16 v66, v0 offset:256
	v_mul_f32_e32 v0, v17, v16
	v_cvt_pk_bf16_f32 v0, v0, v0
	ds_write_b16 v66, v0 offset:320
	v_mul_f32_e32 v0, v33, v16
	v_cvt_pk_bf16_f32 v0, v0, v0
	ds_write_b16 v66, v0 offset:384
	v_mul_f32_e32 v0, v49, v16
	v_cvt_pk_bf16_f32 v0, v0, v0
	ds_read_b32 v1, v68 offset:8
	ds_write_b16 v66, v0 offset:448
	s_waitcnt lgkmcnt(1)
	v_rcp_f32_e32 v1, v1
	s_nop 0
	v_mul_f32_e32 v0, v2, v1
	v_cvt_pk_bf16_f32 v0, v0, v0
	ds_write_b16 v66, v0 offset:512
	v_mul_f32_e32 v0, v18, v1
	v_cvt_pk_bf16_f32 v0, v0, v0
	ds_write_b16 v66, v0 offset:576
	v_mul_f32_e32 v0, v34, v1
	v_cvt_pk_bf16_f32 v0, v0, v0
	ds_write_b16 v66, v0 offset:640
	v_mul_f32_e32 v0, v50, v1
	v_cvt_pk_bf16_f32 v0, v0, v0
	ds_read_b32 v1, v68 offset:12
	ds_write_b16 v66, v0 offset:704
	v_lshlrev_b32_e32 v2, 5, v70
	s_waitcnt lgkmcnt(1)
	v_rcp_f32_e32 v1, v1
	s_nop 0
	v_mul_f32_e32 v0, v3, v1
	v_cvt_pk_bf16_f32 v0, v0, v0
	ds_write_b16 v66, v0 offset:768
	v_mul_f32_e32 v0, v19, v1
	v_cvt_pk_bf16_f32 v0, v0, v0
	ds_write_b16 v66, v0 offset:832
	v_mul_f32_e32 v0, v35, v1
	v_cvt_pk_bf16_f32 v0, v0, v0
	ds_write_b16 v66, v0 offset:896
	v_mul_f32_e32 v0, v51, v1
	v_cvt_pk_bf16_f32 v0, v0, v0
	ds_read_b32 v1, v68 offset:32
	ds_write_b16 v66, v0 offset:960
	s_waitcnt lgkmcnt(1)
	v_rcp_f32_e32 v1, v1
	s_nop 0
	v_mul_f32_e32 v0, v4, v1
	v_cvt_pk_bf16_f32 v0, v0, v0
	ds_write_b16 v66, v0 offset:2048
	v_mul_f32_e32 v0, v20, v1
	v_cvt_pk_bf16_f32 v0, v0, v0
	ds_write_b16 v66, v0 offset:2112
	v_mul_f32_e32 v0, v36, v1
	v_cvt_pk_bf16_f32 v0, v0, v0
	ds_write_b16 v66, v0 offset:2176
	v_mul_f32_e32 v0, v52, v1
	v_cvt_pk_bf16_f32 v0, v0, v0
	ds_read_b32 v1, v68 offset:36
	ds_write_b16 v66, v0 offset:2240
	v_lshrrev_b32_e32 v4, 4, v65
	s_waitcnt lgkmcnt(1)
	v_rcp_f32_e32 v1, v1
	s_nop 0
	v_mul_f32_e32 v0, v5, v1
	v_cvt_pk_bf16_f32 v0, v0, v0
	ds_write_b16 v66, v0 offset:2304
	v_mul_f32_e32 v0, v21, v1
	v_cvt_pk_bf16_f32 v0, v0, v0
	ds_write_b16 v66, v0 offset:2368
	v_mul_f32_e32 v0, v37, v1
	v_cvt_pk_bf16_f32 v0, v0, v0
	ds_write_b16 v66, v0 offset:2432
	v_mul_f32_e32 v0, v53, v1
	v_cvt_pk_bf16_f32 v0, v0, v0
	ds_read_b32 v1, v68 offset:40
	ds_write_b16 v66, v0 offset:2496
	s_waitcnt lgkmcnt(1)
	v_rcp_f32_e32 v1, v1
	s_nop 0
	v_mul_f32_e32 v0, v6, v1
	v_cvt_pk_bf16_f32 v0, v0, v0
	ds_write_b16 v66, v0 offset:2560
	v_mul_f32_e32 v0, v22, v1
	v_cvt_pk_bf16_f32 v0, v0, v0
	ds_write_b16 v66, v0 offset:2624
	v_mul_f32_e32 v0, v38, v1
	v_cvt_pk_bf16_f32 v0, v0, v0
	ds_write_b16 v66, v0 offset:2688
	v_mul_f32_e32 v0, v54, v1
	v_cvt_pk_bf16_f32 v0, v0, v0
	ds_read_b32 v1, v68 offset:44
	ds_write_b16 v66, v0 offset:2752
	s_waitcnt lgkmcnt(1)
	v_rcp_f32_e32 v1, v1
	s_nop 0
	v_mul_f32_e32 v0, v7, v1
	v_cvt_pk_bf16_f32 v0, v0, v0
	ds_write_b16 v66, v0 offset:2816
	v_mul_f32_e32 v0, v23, v1
	v_cvt_pk_bf16_f32 v0, v0, v0
	ds_write_b16 v66, v0 offset:2880
	v_mul_f32_e32 v0, v39, v1
	v_cvt_pk_bf16_f32 v0, v0, v0
	ds_write_b16 v66, v0 offset:2944
	v_mul_f32_e32 v0, v55, v1
	v_cvt_pk_bf16_f32 v0, v0, v0
	ds_read_b32 v1, v68 offset:64
	ds_write_b16 v66, v0 offset:3008
	s_waitcnt lgkmcnt(1)
	v_rcp_f32_e32 v1, v1
	s_nop 0
	v_mul_f32_e32 v0, v8, v1
	v_cvt_pk_bf16_f32 v0, v0, v0
	ds_write_b16 v66, v0 offset:4096
	v_mul_f32_e32 v0, v24, v1
	v_cvt_pk_bf16_f32 v0, v0, v0
	ds_write_b16 v66, v0 offset:4160
	v_mul_f32_e32 v0, v40, v1
	v_cvt_pk_bf16_f32 v0, v0, v0
	ds_write_b16 v66, v0 offset:4224
	v_mul_f32_e32 v0, v56, v1
	v_cvt_pk_bf16_f32 v0, v0, v0
	ds_read_b32 v1, v68 offset:68
	ds_write_b16 v66, v0 offset:4288
	s_waitcnt lgkmcnt(1)
	v_rcp_f32_e32 v1, v1
	s_nop 0
	v_mul_f32_e32 v0, v9, v1
	v_cvt_pk_bf16_f32 v0, v0, v0
	ds_write_b16 v66, v0 offset:4352
	v_mul_f32_e32 v0, v25, v1
	v_cvt_pk_bf16_f32 v0, v0, v0
	ds_write_b16 v66, v0 offset:4416
	v_mul_f32_e32 v0, v41, v1
	v_cvt_pk_bf16_f32 v0, v0, v0
	ds_write_b16 v66, v0 offset:4480
	v_mul_f32_e32 v0, v57, v1
	v_cvt_pk_bf16_f32 v0, v0, v0
	ds_read_b32 v1, v68 offset:72
	ds_write_b16 v66, v0 offset:4544
	s_waitcnt lgkmcnt(1)
	v_rcp_f32_e32 v1, v1
	s_nop 0
	v_mul_f32_e32 v0, v10, v1
	v_cvt_pk_bf16_f32 v0, v0, v0
	ds_write_b16 v66, v0 offset:4608
	v_mul_f32_e32 v0, v26, v1
	v_cvt_pk_bf16_f32 v0, v0, v0
	ds_write_b16 v66, v0 offset:4672
	v_mul_f32_e32 v0, v42, v1
	v_cvt_pk_bf16_f32 v0, v0, v0
	ds_write_b16 v66, v0 offset:4736
	v_mul_f32_e32 v0, v58, v1
	v_cvt_pk_bf16_f32 v0, v0, v0
	ds_read_b32 v1, v68 offset:76
	ds_write_b16 v66, v0 offset:4800
	s_waitcnt lgkmcnt(1)
	v_rcp_f32_e32 v1, v1
	s_nop 0
	v_mul_f32_e32 v0, v11, v1
	v_cvt_pk_bf16_f32 v0, v0, v0
	ds_write_b16 v66, v0 offset:4864
	v_mul_f32_e32 v0, v27, v1
	v_cvt_pk_bf16_f32 v0, v0, v0
	ds_write_b16 v66, v0 offset:4928
	v_mul_f32_e32 v0, v43, v1
	v_cvt_pk_bf16_f32 v0, v0, v0
	ds_write_b16 v66, v0 offset:4992
	v_mul_f32_e32 v0, v59, v1
	v_cvt_pk_bf16_f32 v0, v0, v0
	ds_read_b32 v1, v68 offset:96
	ds_write_b16 v66, v0 offset:5056
	s_waitcnt lgkmcnt(1)
;     ...
;     float l_reg = 0, dummy_m = 0, dummy_a = 1.f; f32x16 o[4] = {}; bf16x8 qr[NREG];
;     char* qs = lds + OFF_Q + wid * (2 * 1024) + lane * 16;
;     {
;         const bf16_t* Qw = Qb + (size_t)(wid * QBLK + r32) * LDQ + hi * 8;
; #pragma unroll
;         for (int d0 = 0; d0 < NREG; ++d0) qr[d0] = *(const bf16x8*)(Qw + d0 * 16);
; #pragma unroll
;         for (int d0 = NREG; d0 < ND0; ++d0) *(bf16x8*)(qs + (d0 - NREG) * 1024) = *(const bf16x8*)(Qw + d0 * 16);
;     }
;     const int widu = __builtin_amdgcn_readfirstlane(wid);
;     const int vb0 = (int)(uintptr_t)V_lds + v_rd_base(lane);
;     unsigned ksrc[2], vsrc[2];
; #pragma unroll
;     for (int i = 0; i < 2; ++i) {
;         if (DQK == 128) { const int j = wid * 2 + i, row = 4 * j + (lane >> 4), c = (lane & 15) ^ (row & 15); ksrc[i] = (unsigned)(row * LDK + c * 8) * 2u; }
;         else { const int row = 8 * wid + (lane >> 3), c = (lane & 7) ^ ((row >> 1) & 7); ksrc[i] = (unsigned)(row * LDK + c * 8) * 2u; }
;         const int j = wid * 2 + i, st = 2 * j + (lane >> 5), kk = (st >> 2) * 8 + ((lane & 31) >> 2), c = (st & 3) * 32 + (lane & 3) * 8;
;         const int k = (kk & ~0xC) | ((kk & 4) << 1) | ((kk & 8) >> 1);
;     ...
;         asm volatile("s_waitcnt lgkmcnt(0)" ::: "memory");
;         if (mode != 1) {
;             bf16_t* Ow = Ob + (size_t)(wid2 * QBLK) * LDO;
;             const int ch = lane2 & 15;
;             float gg[8];
;             if (mode == 2) {
; #pragma unroll
;                 for (int e = 0; e < 8; ++e) gg[e] = sg[ch * 8 + e] * 0.8f; }
; #pragma unroll
;             for (int i = 0; i < 8; ++i) { const int row = i * 4 + (lane2 >> 4); u32x4 v = *(const u32x4*)(stg + row * 128 + ch * 8);
;                 if (mode == 2) { const u32x4 v0 = *(const u32x4*)(stash + row * 128 + ch * 8); float x0[8], x1[8]; unpack8(v0, x0); unpack8(v, x1); float ss = 0.f;
; #pragma unroll
;                     for (int e = 0; e < 8; ++e) { x0[e] = x0[e] - lam * x1[e]; ss += x0[e] * x0[e]; }
;                     ss += __shfl_xor(ss, 1); ss += __shfl_xor(ss, 2); ss += __shfl_xor(ss, 4); ss += __shfl_xor(ss, 8);
;                     const float rstd = rsqrtf(ss * (1.0f / 128) + EPS);
; #pragma unroll
;                     for (int e = 0; e < 8; ++e) x0[e] = x0[e] * rstd * gg[e];
;                     v = pack8(x0); }
;                 *(u32x4*)(Ow + (size_t)row * LDO + ch * 8) = v; }
	v_rcp_f32_e32 v1, v1
	s_nop 0
	v_mul_f32_e32 v0, v12, v1
	v_cvt_pk_bf16_f32 v0, v0, v0
	ds_write_b16 v66, v0 offset:6144
	v_mul_f32_e32 v0, v28, v1
	v_cvt_pk_bf16_f32 v0, v0, v0
	ds_write_b16 v66, v0 offset:6208
	v_mul_f32_e32 v0, v44, v1
	v_cvt_pk_bf16_f32 v0, v0, v0
	ds_write_b16 v66, v0 offset:6272
	v_mul_f32_e32 v0, v60, v1
	v_cvt_pk_bf16_f32 v0, v0, v0
	ds_read_b32 v1, v68 offset:100
	ds_write_b16 v66, v0 offset:6336
	s_waitcnt lgkmcnt(1)
	v_rcp_f32_e32 v1, v1
	s_nop 0
	v_mul_f32_e32 v0, v13, v1
	v_cvt_pk_bf16_f32 v0, v0, v0
	ds_write_b16 v66, v0 offset:6400
	v_mul_f32_e32 v0, v29, v1
	v_cvt_pk_bf16_f32 v0, v0, v0
	ds_write_b16 v66, v0 offset:6464
	v_mul_f32_e32 v0, v45, v1
	v_cvt_pk_bf16_f32 v0, v0, v0
	ds_write_b16 v66, v0 offset:6528
	v_mul_f32_e32 v0, v61, v1
	v_cvt_pk_bf16_f32 v0, v0, v0
	ds_read_b32 v1, v68 offset:104
	ds_write_b16 v66, v0 offset:6592
	s_waitcnt lgkmcnt(1)
	v_rcp_f32_e32 v1, v1
	s_nop 0
	v_mul_f32_e32 v0, v14, v1
	v_cvt_pk_bf16_f32 v0, v0, v0
	ds_write_b16 v66, v0 offset:6656
	v_mul_f32_e32 v0, v30, v1
	v_cvt_pk_bf16_f32 v0, v0, v0
	ds_write_b16 v66, v0 offset:6720
	v_mul_f32_e32 v0, v46, v1
	v_cvt_pk_bf16_f32 v0, v0, v0
	ds_write_b16 v66, v0 offset:6784
	v_mul_f32_e32 v0, v62, v1
	v_cvt_pk_bf16_f32 v0, v0, v0
	ds_read_b32 v1, v68 offset:108
	ds_write_b16 v66, v0 offset:6848
	s_waitcnt lgkmcnt(1)
	v_rcp_f32_e32 v1, v1
	s_nop 0
	v_mul_f32_e32 v0, v15, v1
	v_cvt_pk_bf16_f32 v0, v0, v0
	ds_write_b16 v66, v0 offset:6912
	v_mul_f32_e32 v0, v31, v1
	v_cvt_pk_bf16_f32 v0, v0, v0
	ds_write_b16 v66, v0 offset:6976
	v_mul_f32_e32 v0, v47, v1
	v_cvt_pk_bf16_f32 v0, v0, v0
	ds_write_b16 v66, v0 offset:7040
	v_mul_f32_e32 v0, v63, v1
	v_cvt_pk_bf16_f32 v0, v0, v0
	ds_write_b16 v66, v0 offset:7104
	v_mov_b64_e32 v[0:1], s[42:43]
	v_mad_i64_i32 v[0:1], s[0:1], v2, s33, v[0:1]
	v_lshlrev_b32_e32 v2, 4, v64
	v_and_b32_e32 v160, 0xf0, v2
	v_lshl_add_u64 v[8:9], v[0:1], 0, v[160:161]
	v_lshlrev_b32_e32 v0, 8, v4
	s_waitcnt lgkmcnt(0)
	v_add3_u32 v14, v71, v160, v0
	ds_read_b128 v[0:3], v14
	v_mul_u32_u24_e32 v4, 0x1c00, v4
	v_lshlrev_b32_e32 v160, 1, v4
	ds_read_b128 v[4:7], v14 offset:1024
	v_lshl_add_u64 v[10:11], v[8:9], 0, v[160:161]
	s_waitcnt lgkmcnt(1)
	global_store_dwordx4 v[10:11], v[0:3], off nt
	s_nop 1
	v_add_co_u32_e32 v0, vcc, s47, v10
	s_nop 1
	v_addc_co_u32_e32 v1, vcc, 0, v11, vcc
	s_waitcnt lgkmcnt(0)
	global_store_dwordx4 v[0:1], v[4:7], off nt
	ds_read_b128 v[0:3], v14 offset:2048
	ds_read_b128 v[4:7], v14 offset:3072
	v_add_co_u32_e32 v12, vcc, s48, v10
	s_nop 1
	v_addc_co_u32_e32 v13, vcc, 0, v11, vcc
	s_waitcnt lgkmcnt(1)
	global_store_dwordx4 v[12:13], v[0:3], off nt
	s_nop 1
	v_add_co_u32_e32 v0, vcc, s49, v10
	s_nop 1
	v_addc_co_u32_e32 v1, vcc, 0, v11, vcc
	s_waitcnt lgkmcnt(0)
	global_store_dwordx4 v[0:1], v[4:7], off nt
	ds_read_b128 v[0:3], v14 offset:4096
	s_nop 0
	v_add_u32_e32 v4, 0x38000, v160
	v_mov_b32_e32 v5, v161
	v_lshl_add_u64 v[10:11], v[8:9], 0, v[4:5]
	ds_read_b128 v[4:7], v14 offset:5120
	s_waitcnt lgkmcnt(1)
	global_store_dwordx4 v[10:11], v[0:3], off nt
	v_add_u32_e32 v10, 0x54000, v160
	v_mov_b32_e32 v11, v161
	v_add_u32_e32 v0, 0x46000, v160
	v_mov_b32_e32 v1, v161
	v_lshl_add_u64 v[0:1], v[8:9], 0, v[0:1]
	s_waitcnt lgkmcnt(0)
	global_store_dwordx4 v[0:1], v[4:7], off nt
	ds_read_b128 v[0:3], v14 offset:6144
	ds_read_b128 v[4:7], v14 offset:7168
	v_lshl_add_u64 v[10:11], v[8:9], 0, v[10:11]
	v_add_u32_e32 v160, 0x62000, v160
	s_waitcnt lgkmcnt(1)
	global_store_dwordx4 v[10:11], v[0:3], off nt
	s_nop 1
	v_lshl_add_u64 v[0:1], v[8:9], 0, v[160:161]
	s_waitcnt lgkmcnt(0)
	global_store_dwordx4 v[0:1], v[4:7], off nt
	s_nop 0
	s_barrier
	s_cbranch_scc1 .LBB0_532
.LBB0_526:
	s_ashr_i32 s45, s51, 8
	s_lshl_b32 s1, s51, 8
	s_lshl_b32 s0, s45, 12
	s_and_b32 s1, s1, 0xf00
	s_or_b32 s0, s0, s1
	s_bfe_u32 s52, s51, 0x20006
	s_mul_hi_i32 s1, s0, 0x3800
	s_mulk_i32 s0, 0x3800
	s_add_u32 s0, s12, s0
	s_addc_u32 s1, s13, s1
	s_lshl_b32 s42, s51, 4
	s_and_b32 s42, s42, 0x300
	s_lshl_b32 s43, s52, 10
	s_or_b32 s42, s43, s42
	s_add_u32 s42, s0, s42
	v_mov_b32_e32 v2, v218
	s_addc_u32 s43, s1, 0
	v_mov_b64_e32 v[4:5], s[42:43]
	v_ashrrev_i32_e32 v14, 6, v2
	v_and_b32_e32 v0, 31, v2
	v_bfe_u32 v1, v2, 5, 1
	v_lshl_or_b32 v3, v14, 5, v0
	v_mad_i64_i32 v[4:5], s[0:1], v3, s33, v[4:5]
	v_lshlrev_b32_e32 v16, 4, v1
	v_mov_b32_e32 v17, v161
	v_lshl_add_u64 v[4:5], v[4:5], 0, v[16:17]
	global_load_dwordx4 v[6:9], v[4:5], off offset:192 nt
	global_load_dwordx4 v[10:13], v[4:5], off offset:224 nt
	global_load_dwordx4 v[116:119], v[4:5], off nt
	global_load_dwordx4 v[112:115], v[4:5], off offset:32 nt
	global_load_dwordx4 v[108:111], v[4:5], off offset:64 nt
	global_load_dwordx4 v[104:107], v[4:5], off offset:96 nt
	global_load_dwordx4 v[100:103], v[4:5], off offset:128 nt
	global_load_dwordx4 v[96:99], v[4:5], off offset:160 nt
	v_and_b32_e32 v4, 63, v2
	v_bfe_u32 v15, v2, 4, 2
	v_lshlrev_b32_e32 v3, 3, v14
	s_movk_i32 s0, 0xc00
	s_mul_hi_i32 s44, s45, 0x1980000
	s_mul_i32 s45, s45, 0x1980000
	v_lshlrev_b32_e32 v5, 4, v4
	v_lshl_add_u32 v17, v14, 11, s34
	v_readfirstlane_b32 s53, v14
	v_or_b32_e32 v14, v3, v15
	v_add_u32_e32 v229, v17, v5
	v_mul_lo_u32 v17, v14, s0
	s_add_u32 s0, s10, s45
	s_addc_u32 s1, s11, s44
	s_lshl_b32 s52, s52, 8
	s_add_u32 s0, s0, s52
	v_bitop3_b32 v15, v3, v2, v15 bitop3:0x36
	s_addc_u32 s1, s1, 0
	s_lshl_b32 s52, s53, 11
	v_lshlrev_b32_e32 v15, 3, v15
	v_bitop3_b32 v14, v14, v2, 4 bitop3:0x36
	s_cmp_lg_u32 0, -1
	v_and_or_b32 v15, v15, s35, v17
	v_lshlrev_b32_e32 v14, 3, v14
	s_cselect_b32 s53, 0, 0
	v_lshlrev_b32_e32 v160, 1, v15
	v_and_or_b32 v14, v14, s35, v17
	s_add_i32 s54, s53, s52
	v_mov_b32_e32 v163, v161
	v_lshl_add_u32 v162, v14, 1, v226
	v_lshl_add_u64 v[14:15], s[0:1], 0, v[160:161]
	s_add_i32 s53, s54, 0x8000
	v_lshl_add_u64 v[18:19], s[0:1], 0, v[162:163]
	s_add_i32 s54, s54, 0x8400
	s_waitcnt vmcnt(7)
	ds_write_b128 v229, v[6:9]
	s_waitcnt vmcnt(6)
	ds_write_b128 v229, v[10:13] offset:1024
	s_mov_b32 s55, m0
	s_mov_b32 m0, s53
	s_nop 0
	global_load_lds_dwordx4 v[14:15], off
	s_mov_b32 m0, s55
	s_nop 0
	s_mov_b32 s55, m0
	s_mov_b32 m0, s54
	s_nop 0
	global_load_lds_dwordx4 v[18:19], off
	s_mov_b32 m0, s55
	s_waitcnt vmcnt(0)
	s_waitcnt lgkmcnt(0)
	v_readfirstlane_b32 s55, v2
	s_cmpk_lt_i32 s55, 0x100
	s_barrier
	s_cbranch_scc1 .LBB0_528
	s_setprio 1

; __device__ __forceinline__ unsigned cvt_pk_bf16(float lo, float hi) { unsigned r; asm volatile("v_cvt_pk_bf16_f32 %0, %1, %2" : "=v"(r) : "v"(lo), "v"(hi)); return r; }
; __device__ __forceinline__ int crow(int r, int hi) { return (r & 3) + 8 * (r >> 2) + 4 * hi; }
;     ...
;         if (hib == 0) li2[r32b] = l_reg; asm volatile("s_waitcnt lgkmcnt(0)" ::: "memory");
;         __syncthreads();
;         bf16_t* stash = (bf16_t*)(lds + OFF_Q) + wid2 * 4096;
;         bf16_t* stg = (mode == 1) ? stash : ((bf16_t*)lds + wid2 * 4096);
; #pragma unroll
;         for (int r = 0; r < 16; ++r) { const int orow = crow(r, hib); const float rl = __builtin_amdgcn_rcpf(li2[orow]);
; #pragma unroll
;             for (int d0 = 0; d0 < 4; ++d0) { const float v = o[d0][r] * rl; stg[orow * 128 + d0 * 32 + r32b] = (bf16_t)(cvt_pk_bf16(v, v) & 0xffffu); } }
.LBB0_557:
	s_or_b64 exec, exec, s[0:1]
	v_lshrrev_b32_e32 v66, 3, v65
	v_and_b32_e32 v66, 4, v66
	v_lshl_add_u32 v68, v66, 2, v68
	s_waitcnt lgkmcnt(0)
	s_waitcnt lgkmcnt(0)
	s_barrier
	ds_read_b32 v69, v68
	v_ashrrev_i32_e32 v70, 6, v65
	v_lshlrev_b32_e32 v71, 13, v70
	v_add_u32_e32 v72, 0, v71
	v_lshlrev_b32_e32 v67, 1, v67
	s_waitcnt lgkmcnt(0)
	v_rcp_f32_e32 v69, v69
	v_lshlrev_b32_e32 v66, 8, v66
	v_add3_u32 v66, v72, v67, v66
	s_movk_i32 s0, 0x3800
	v_mul_f32_e32 v0, v0, v69
	v_cvt_pk_bf16_f32 v0, v0, v0
	ds_write_b16 v66, v0
	v_mul_f32_e32 v0, v16, v69
	v_cvt_pk_bf16_f32 v0, v0, v0
	ds_write_b16 v66, v0 offset:64
	v_mul_f32_e32 v0, v32, v69
	v_cvt_pk_bf16_f32 v0, v0, v0
	ds_write_b16 v66, v0 offset:128
	v_mul_f32_e32 v0, v48, v69
	v_cvt_pk_bf16_f32 v0, v0, v0
	ds_read_b32 v16, v68 offset:4
	ds_write_b16 v66, v0 offset:192
	s_add_i32 s54, s54, s15
	s_add_i32 s33, s33, s34
	s_cmpk_gt_i32 s54, 0x1ff
	s_waitcnt lgkmcnt(1)
	v_rcp_f32_e32 v16, v16
	s_nop 0
	v_mul_f32_e32 v0, v1, v16
	v_cvt_pk_bf16_f32 v0, v0, v0
	ds_write_b16 v66, v0 offset:256
	v_mul_f32_e32 v0, v17, v16
	v_cvt_pk_bf16_f32 v0, v0, v0
	ds_write_b16 v66, v0 offset:320
	v_mul_f32_e32 v0, v33, v16
	v_cvt_pk_bf16_f32 v0, v0, v0
	ds_write_b16 v66, v0 offset:384
	v_mul_f32_e32 v0, v49, v16
	v_cvt_pk_bf16_f32 v0, v0, v0
	ds_read_b32 v1, v68 offset:8
	ds_write_b16 v66, v0 offset:448
	s_waitcnt lgkmcnt(1)
	v_rcp_f32_e32 v1, v1
	s_nop 0
	v_mul_f32_e32 v0, v2, v1
	v_cvt_pk_bf16_f32 v0, v0, v0
	ds_write_b16 v66, v0 offset:512
	v_mul_f32_e32 v0, v18, v1
	v_cvt_pk_bf16_f32 v0, v0, v0
	ds_write_b16 v66, v0 offset:576
	v_mul_f32_e32 v0, v34, v1
	v_cvt_pk_bf16_f32 v0, v0, v0
	ds_write_b16 v66, v0 offset:640
	v_mul_f32_e32 v0, v50, v1
	v_cvt_pk_bf16_f32 v0, v0, v0
	ds_read_b32 v1, v68 offset:12
	ds_write_b16 v66, v0 offset:704
	s_waitcnt lgkmcnt(1)
	v_rcp_f32_e32 v1, v1
	s_nop 0
	v_mul_f32_e32 v0, v3, v1
	v_cvt_pk_bf16_f32 v0, v0, v0
	ds_write_b16 v66, v0 offset:768
	v_mul_f32_e32 v0, v19, v1
	v_cvt_pk_bf16_f32 v0, v0, v0
	ds_write_b16 v66, v0 offset:832
	v_mul_f32_e32 v0, v35, v1
	v_cvt_pk_bf16_f32 v0, v0, v0
	ds_write_b16 v66, v0 offset:896
	v_mul_f32_e32 v0, v51, v1
	v_cvt_pk_bf16_f32 v0, v0, v0
	ds_read_b32 v1, v68 offset:32
	ds_write_b16 v66, v0 offset:960
	s_waitcnt lgkmcnt(1)
	v_rcp_f32_e32 v1, v1
	s_nop 0
	v_mul_f32_e32 v0, v4, v1
	v_cvt_pk_bf16_f32 v0, v0, v0
	ds_write_b16 v66, v0 offset:2048
	v_mul_f32_e32 v0, v20, v1
	v_cvt_pk_bf16_f32 v0, v0, v0
	ds_write_b16 v66, v0 offset:2112
	v_mul_f32_e32 v0, v36, v1
	v_cvt_pk_bf16_f32 v0, v0, v0
	ds_write_b16 v66, v0 offset:2176
	v_mul_f32_e32 v0, v52, v1
	v_cvt_pk_bf16_f32 v0, v0, v0
	ds_read_b32 v1, v68 offset:36
	ds_write_b16 v66, v0 offset:2240
	s_waitcnt lgkmcnt(1)
	v_rcp_f32_e32 v1, v1
	s_nop 0
	v_mul_f32_e32 v0, v5, v1
	v_cvt_pk_bf16_f32 v0, v0, v0
	ds_write_b16 v66, v0 offset:2304
	v_mul_f32_e32 v0, v21, v1
	v_cvt_pk_bf16_f32 v0, v0, v0
	ds_write_b16 v66, v0 offset:2368
	v_mul_f32_e32 v0, v37, v1
	v_cvt_pk_bf16_f32 v0, v0, v0
	ds_write_b16 v66, v0 offset:2432
	v_mul_f32_e32 v0, v53, v1
	v_cvt_pk_bf16_f32 v0, v0, v0
	ds_read_b32 v1, v68 offset:40
	ds_write_b16 v66, v0 offset:2496
	s_waitcnt lgkmcnt(1)
	v_rcp_f32_e32 v1, v1
	s_nop 0
	v_mul_f32_e32 v0, v6, v1
	v_cvt_pk_bf16_f32 v0, v0, v0
	ds_write_b16 v66, v0 offset:2560
	v_mul_f32_e32 v0, v22, v1
	v_cvt_pk_bf16_f32 v0, v0, v0
	ds_write_b16 v66, v0 offset:2624
	v_mul_f32_e32 v0, v38, v1
	v_cvt_pk_bf16_f32 v0, v0, v0
	ds_write_b16 v66, v0 offset:2688
	v_mul_f32_e32 v0, v54, v1
	v_cvt_pk_bf16_f32 v0, v0, v0
	ds_read_b32 v1, v68 offset:44
	ds_write_b16 v66, v0 offset:2752
	s_waitcnt lgkmcnt(1)
	v_rcp_f32_e32 v1, v1
	s_nop 0
	v_mul_f32_e32 v0, v7, v1
	v_cvt_pk_bf16_f32 v0, v0, v0
	ds_write_b16 v66, v0 offset:2816
	v_mul_f32_e32 v0, v23, v1
	v_cvt_pk_bf16_f32 v0, v0, v0
	ds_write_b16 v66, v0 offset:2880
	v_mul_f32_e32 v0, v39, v1
	v_cvt_pk_bf16_f32 v0, v0, v0
	ds_write_b16 v66, v0 offset:2944
	v_mul_f32_e32 v0, v55, v1
	v_cvt_pk_bf16_f32 v0, v0, v0
	ds_read_b32 v1, v68 offset:64
	ds_write_b16 v66, v0 offset:3008
	v_lshrrev_b32_e32 v23, 4, v64
	v_lshlrev_b32_e32 v22, 8, v23
	s_waitcnt lgkmcnt(1)
	v_rcp_f32_e32 v1, v1
	s_nop 0
	v_mul_f32_e32 v0, v8, v1
	v_cvt_pk_bf16_f32 v0, v0, v0
	ds_write_b16 v66, v0 offset:4096
	v_mul_f32_e32 v0, v24, v1
	v_cvt_pk_bf16_f32 v0, v0, v0
	ds_write_b16 v66, v0 offset:4160
	v_mul_f32_e32 v0, v40, v1
	v_cvt_pk_bf16_f32 v0, v0, v0
	ds_write_b16 v66, v0 offset:4224
	v_mul_f32_e32 v0, v56, v1
	v_cvt_pk_bf16_f32 v0, v0, v0
	ds_read_b32 v1, v68 offset:68
	ds_write_b16 v66, v0 offset:4288
	s_waitcnt lgkmcnt(1)
	v_rcp_f32_e32 v1, v1
	s_nop 0
	v_mul_f32_e32 v0, v9, v1
	v_cvt_pk_bf16_f32 v0, v0, v0
	ds_write_b16 v66, v0 offset:4352
	v_mul_f32_e32 v0, v25, v1
	v_cvt_pk_bf16_f32 v0, v0, v0
	ds_write_b16 v66, v0 offset:4416
	v_mul_f32_e32 v0, v41, v1
	v_cvt_pk_bf16_f32 v0, v0, v0
	ds_write_b16 v66, v0 offset:4480
	v_mul_f32_e32 v0, v57, v1
	v_cvt_pk_bf16_f32 v0, v0, v0
	ds_read_b32 v1, v68 offset:72
	ds_write_b16 v66, v0 offset:4544
	s_waitcnt lgkmcnt(1)
	v_rcp_f32_e32 v1, v1
	s_nop 0
	v_mul_f32_e32 v0, v10, v1
	v_cvt_pk_bf16_f32 v0, v0, v0
	ds_write_b16 v66, v0 offset:4608
	v_mul_f32_e32 v0, v26, v1
	v_cvt_pk_bf16_f32 v0, v0, v0
	ds_write_b16 v66, v0 offset:4672
	v_mul_f32_e32 v0, v42, v1
	v_cvt_pk_bf16_f32 v0, v0, v0
	ds_write_b16 v66, v0 offset:4736
	v_mul_f32_e32 v0, v58, v1
	v_cvt_pk_bf16_f32 v0, v0, v0
	ds_read_b32 v1, v68 offset:76
	ds_write_b16 v66, v0 offset:4800
	s_waitcnt lgkmcnt(1)
; __device__ __forceinline__ unsigned cvt_pk_bf16(float lo, float hi) { unsigned r; asm volatile("v_cvt_pk_bf16_f32 %0, %1, %2" : "=v"(r) : "v"(lo), "v"(hi)); return r; }
; __device__ __forceinline__ int crow(int r, int hi) { return (r & 3) + 8 * (r >> 2) + 4 * hi; }
;     ...
;         for (int r = 0; r < 16; ++r) { const int orow = crow(r, hib); const float rl = __builtin_amdgcn_rcpf(li2[orow]);
; #pragma unroll
;             for (int d0 = 0; d0 < 4; ++d0) { const float v = o[d0][r] * rl; stg[orow * 128 + d0 * 32 + r32b] = (bf16_t)(cvt_pk_bf16(v, v) & 0xffffu); } }
;         asm volatile("s_waitcnt lgkmcnt(0)" ::: "memory");
;         if (mode != 1) {
;             bf16_t* Ow = Ob + (size_t)(wid2 * QBLK) * LDO;
;             const int ch = lane2 & 15;
;             float gg[8];
;             if (mode == 2) {
; #pragma unroll
;                 for (int e = 0; e < 8; ++e) gg[e] = sg[ch * 8 + e] * 0.8f; }
; #pragma unroll
;             for (int i = 0; i < 8; ++i) { const int row = i * 4 + (lane2 >> 4); u32x4 v = *(const u32x4*)(stg + row * 128 + ch * 8);
;                 if (mode == 2) { const u32x4 v0 = *(const u32x4*)(stash + row * 128 + ch * 8); float x0[8], x1[8]; unpack8(v0, x0); unpack8(v, x1); float ss = 0.f;
; #pragma unroll
;                     for (int e = 0; e < 8; ++e) { x0[e] = x0[e] - lam * x1[e]; ss += x0[e] * x0[e]; }
;                     ss += __shfl_xor(ss, 1); ss += __shfl_xor(ss, 2); ss += __shfl_xor(ss, 4); ss += __shfl_xor(ss, 8);
;                     const float rstd = rsqrtf(ss * (1.0f / 128) + EPS);
; #pragma unroll
;                     for (int e = 0; e < 8; ++e) x0[e] = x0[e] * rstd * gg[e];
;                     v = pack8(x0); }
;                 *(u32x4*)(Ow + (size_t)row * LDO + ch * 8) = v; }
	v_rcp_f32_e32 v1, v1
	s_nop 0
	v_mul_f32_e32 v0, v11, v1
	v_cvt_pk_bf16_f32 v0, v0, v0
	ds_write_b16 v66, v0 offset:4864
	v_mul_f32_e32 v0, v27, v1
	v_cvt_pk_bf16_f32 v0, v0, v0
	ds_write_b16 v66, v0 offset:4928
	v_mul_f32_e32 v0, v43, v1
	v_cvt_pk_bf16_f32 v0, v0, v0
	ds_write_b16 v66, v0 offset:4992
	v_mul_f32_e32 v0, v59, v1
	v_cvt_pk_bf16_f32 v0, v0, v0
	ds_read_b32 v1, v68 offset:96
	ds_write_b16 v66, v0 offset:5056
	s_waitcnt lgkmcnt(1)
	v_rcp_f32_e32 v1, v1
	s_nop 0
	v_mul_f32_e32 v0, v12, v1
	v_cvt_pk_bf16_f32 v0, v0, v0
	ds_write_b16 v66, v0 offset:6144
	v_mul_f32_e32 v0, v28, v1
	v_cvt_pk_bf16_f32 v0, v0, v0
	ds_write_b16 v66, v0 offset:6208
	v_mul_f32_e32 v0, v44, v1
	v_cvt_pk_bf16_f32 v0, v0, v0
	ds_write_b16 v66, v0 offset:6272
	v_mul_f32_e32 v0, v60, v1
	v_cvt_pk_bf16_f32 v0, v0, v0
	ds_read_b32 v1, v68 offset:100
	ds_write_b16 v66, v0 offset:6336
	s_waitcnt lgkmcnt(1)
	v_rcp_f32_e32 v1, v1
	s_nop 0
	v_mul_f32_e32 v0, v13, v1
	v_cvt_pk_bf16_f32 v0, v0, v0
	ds_write_b16 v66, v0 offset:6400
	v_mul_f32_e32 v0, v29, v1
	v_cvt_pk_bf16_f32 v0, v0, v0
	ds_write_b16 v66, v0 offset:6464
	v_mul_f32_e32 v0, v45, v1
	v_cvt_pk_bf16_f32 v0, v0, v0
	ds_write_b16 v66, v0 offset:6528
	v_mul_f32_e32 v0, v61, v1
	v_cvt_pk_bf16_f32 v0, v0, v0
	ds_read_b32 v1, v68 offset:104
	ds_write_b16 v66, v0 offset:6592
	s_waitcnt lgkmcnt(1)
	v_rcp_f32_e32 v1, v1
	s_nop 0
	v_mul_f32_e32 v0, v14, v1
	v_cvt_pk_bf16_f32 v0, v0, v0
	ds_write_b16 v66, v0 offset:6656
	v_mul_f32_e32 v0, v30, v1
	v_cvt_pk_bf16_f32 v0, v0, v0
	ds_write_b16 v66, v0 offset:6720
	v_mul_f32_e32 v0, v46, v1
	v_cvt_pk_bf16_f32 v0, v0, v0
	ds_write_b16 v66, v0 offset:6784
	v_mul_f32_e32 v0, v62, v1
	v_cvt_pk_bf16_f32 v0, v0, v0
	ds_read_b32 v1, v68 offset:108
	ds_write_b16 v66, v0 offset:6848
	s_waitcnt lgkmcnt(1)
	v_rcp_f32_e32 v1, v1
	s_nop 0
	v_mul_f32_e32 v0, v15, v1
	v_cvt_pk_bf16_f32 v0, v0, v0
	ds_write_b16 v66, v0 offset:6912
	v_mul_f32_e32 v0, v31, v1
	v_cvt_pk_bf16_f32 v0, v0, v0
	ds_write_b16 v66, v0 offset:6976
	v_mul_f32_e32 v0, v47, v1
	v_cvt_pk_bf16_f32 v0, v0, v0
	ds_write_b16 v66, v0 offset:7040
	v_mul_f32_e32 v0, v63, v1
	v_cvt_pk_bf16_f32 v0, v0, v0
	ds_write_b16 v66, v0 offset:7104
	v_lshlrev_b32_e32 v0, 3, v65
	v_and_b32_e32 v0, 0x78, v0
	s_waitcnt lgkmcnt(0)
	v_lshlrev_b32_e32 v12, 2, v0
	global_load_dwordx4 v[4:7], v12, s[16:17]
	v_lshlrev_b32_e32 v134, 1, v0
	global_load_dwordx4 v[12:15], v12, s[16:17] offset:16
	v_add_u32_e32 v20, v72, v134
	v_add3_u32 v21, s48, v71, v134
	v_add_u32_e32 v0, v21, v22
	v_add_u32_e32 v8, v20, v22
	ds_read_b128 v[0:3], v0
	ds_read_b128 v[8:11], v8
	s_waitcnt lgkmcnt(1)
	v_lshlrev_b32_e32 v16, 16, v0
	v_and_b32_e32 v0, 0xffff0000, v0
	s_waitcnt lgkmcnt(0)
	v_lshlrev_b32_e32 v17, 16, v8
	v_and_b32_e32 v8, 0xffff0000, v8
	v_fma_f32 v19, -v128, v8, v0
	v_and_b32_e32 v0, 0xffff0000, v1
	v_lshlrev_b32_e32 v1, 16, v1
	v_and_b32_e32 v8, 0xffff0000, v9
	v_lshlrev_b32_e32 v9, 16, v9
	v_fma_f32 v17, -v128, v17, v16
	v_mul_f32_e32 v16, v19, v19
	v_pk_fma_f32 v[8:9], v[128:129], v[8:9], v[0:1] neg_lo:[1,0,0] neg_hi:[1,0,0]
	v_fmac_f32_e32 v16, v17, v17
	v_pk_mul_f32 v[0:1], v[8:9], v[8:9]
	v_and_b32_e32 v24, 0xffff0000, v10
	v_add_f32_e32 v1, v1, v16
	v_add_f32_e32 v16, v0, v1
	v_and_b32_e32 v0, 0xffff0000, v2
	v_lshlrev_b32_e32 v1, 16, v2
	v_lshlrev_b32_e32 v25, 16, v10
	v_pk_fma_f32 v[24:25], v[128:129], v[24:25], v[0:1] neg_lo:[1,0,0] neg_hi:[1,0,0]
	v_and_b32_e32 v2, 0xffff0000, v11
	v_pk_mul_f32 v[0:1], v[24:25], v[24:25]
	s_waitcnt vmcnt(1)
	v_mov_b32_e32 v18, v5
	v_add_f32_e32 v1, v1, v16
	v_add_f32_e32 v10, v0, v1
	v_and_b32_e32 v0, 0xffff0000, v3
	v_lshlrev_b32_e32 v1, 16, v3
	v_lshlrev_b32_e32 v3, 16, v11
	v_pk_fma_f32 v[26:27], v[128:129], v[2:3], v[0:1] neg_lo:[1,0,0] neg_hi:[1,0,0]
	v_mov_b32_e32 v16, v4
	v_pk_mul_f32 v[0:1], v[26:27], v[26:27]
	v_mov_b32_e32 v4, v6
	v_add_f32_e32 v1, v1, v10
	v_add_f32_e32 v0, v0, v1
	ds_bpermute_b32 v1, v220, v0
	v_mov_b32_e32 v5, v9
	v_mov_b32_e32 v6, v7
	v_mov_b32_e32 v7, v8
	s_waitcnt vmcnt(0)
	v_mov_b32_e32 v8, v12
	s_waitcnt lgkmcnt(0)
	v_add_f32_e32 v0, v0, v1
	ds_bpermute_b32 v1, v221, v0
	v_mov_b32_e32 v9, v25
	v_mov_b32_e32 v10, v13
	v_mov_b32_e32 v11, v24
	v_mov_b32_e32 v12, v14
	s_waitcnt lgkmcnt(0)
	v_add_f32_e32 v0, v0, v1
	ds_bpermute_b32 v1, v222, v0
	v_mov_b32_e32 v13, v27
	v_mov_b32_e32 v14, v15
	v_mov_b32_e32 v15, v26
	s_waitcnt lgkmcnt(0)
	v_add_f32_e32 v0, v0, v1
	ds_bpermute_b32 v1, v223, v0
	s_waitcnt lgkmcnt(0)
	v_add_f32_e32 v0, v0, v1
	v_fmamk_f32 v0, v0, 0x3c000000, v209
	v_mul_f32_e32 v1, 0x4b800000, v0
	v_cmp_gt_f32_e32 vcc, s50, v0
	s_nop 1
	v_cndmask_b32_e32 v0, v0, v1, vcc
	v_rsq_f32_e32 v0, v0
	s_nop 0
	v_mul_f32_e32 v1, 0x45800000, v0
	v_cndmask_b32_e32 v141, v0, v1, vcc
	v_pk_mul_f32 v[0:1], v[16:17], v[140:141]
	v_pk_mul_f32 v[2:3], v[18:19], v[140:141]
	v_mul_f32_e32 v1, v0, v1
	v_mul_f32_e32 v3, v2, v3
	v_cvt_pk_bf16_f32 v24, v1, v3
	v_or_b32_e32 v1, 0x400, v22
	v_pk_mul_f32 v[4:5], v[4:5], v[140:141]
	v_pk_mul_f32 v[6:7], v[6:7], v[140:141]
	v_pk_mul_f32 v[8:9], v[8:9], v[140:141]
	v_pk_mul_f32 v[10:11], v[10:11], v[140:141]
	v_pk_mul_f32 v[12:13], v[12:13], v[140:141]
	v_pk_mul_f32 v[14:15], v[14:15], v[140:141]
	v_add_u32_e32 v3, v21, v1
	v_add_u32_e32 v1, v20, v1
	v_mul_f32_e32 v5, v4, v5
	v_mul_f32_e32 v7, v6, v7
	v_mul_f32_e32 v9, v8, v9
	v_mul_f32_e32 v11, v10, v11
	v_mul_f32_e32 v13, v12, v13
	v_mul_f32_e32 v15, v14, v15
	v_cvt_pk_bf16_f32 v25, v5, v7
	v_cvt_pk_bf16_f32 v26, v9, v11
	v_cvt_pk_bf16_f32 v27, v13, v15
	ds_read_b128 v[16:19], v3
	ds_read_b128 v[28:31], v1
	v_lshlrev_b32_e32 v9, 5, v70
	s_waitcnt lgkmcnt(1)
	v_and_b32_e32 v3, 0xffff0000, v16
	s_waitcnt lgkmcnt(0)
;     ...
;             for (int i = 0; i < 8; ++i) { const int row = i * 4 + (lane2 >> 4); u32x4 v = *(const u32x4*)(stg + row * 128 + ch * 8);
;                 if (mode == 2) { const u32x4 v0 = *(const u32x4*)(stash + row * 128 + ch * 8); float x0[8], x1[8]; unpack8(v0, x0); unpack8(v, x1); float ss = 0.f;
; #pragma unroll
;                     for (int e = 0; e < 8; ++e) { x0[e] = x0[e] - lam * x1[e]; ss += x0[e] * x0[e]; }
;                     ss += __shfl_xor(ss, 1); ss += __shfl_xor(ss, 2); ss += __shfl_xor(ss, 4); ss += __shfl_xor(ss, 8);
;                     const float rstd = rsqrtf(ss * (1.0f / 128) + EPS);
; #pragma unroll
;                     for (int e = 0; e < 8; ++e) x0[e] = x0[e] * rstd * gg[e];
;                     v = pack8(x0); }
;                 *(u32x4*)(Ow + (size_t)row * LDO + ch * 8) = v; }
	v_and_b32_e32 v7, 0xffff0000, v28
	v_lshlrev_b32_e32 v1, 16, v16
	v_lshlrev_b32_e32 v5, 16, v28
	v_fma_f32 v3, -v128, v7, v3
	v_and_b32_e32 v16, 0xffff0000, v17
	v_lshlrev_b32_e32 v17, 16, v17
	v_and_b32_e32 v28, 0xffff0000, v29
	v_lshlrev_b32_e32 v29, 16, v29
	v_fma_f32 v1, -v128, v5, v1
	v_mul_f32_e32 v5, v3, v3
	v_pk_fma_f32 v[28:29], v[128:129], v[28:29], v[16:17] neg_lo:[1,0,0] neg_hi:[1,0,0]
	v_fmac_f32_e32 v5, v1, v1
	v_pk_mul_f32 v[16:17], v[28:29], v[28:29]
	v_and_b32_e32 v32, 0xffff0000, v30
	v_add_f32_e32 v5, v17, v5
	v_add_f32_e32 v5, v16, v5
	v_and_b32_e32 v16, 0xffff0000, v18
	v_lshlrev_b32_e32 v17, 16, v18
	v_lshlrev_b32_e32 v33, 16, v30
	v_pk_fma_f32 v[32:33], v[128:129], v[32:33], v[16:17] neg_lo:[1,0,0] neg_hi:[1,0,0]
	v_and_b32_e32 v18, 0xffff0000, v31
	v_pk_mul_f32 v[16:17], v[32:33], v[32:33]
	s_nop 0
	v_add_f32_e32 v5, v17, v5
	v_add_f32_e32 v5, v16, v5
	v_and_b32_e32 v16, 0xffff0000, v19
	v_lshlrev_b32_e32 v17, 16, v19
	v_lshlrev_b32_e32 v19, 16, v31
	v_pk_fma_f32 v[30:31], v[128:129], v[18:19], v[16:17] neg_lo:[1,0,0] neg_hi:[1,0,0]
	s_nop 0
	v_pk_mul_f32 v[16:17], v[30:31], v[30:31]
	s_nop 0
	v_add_f32_e32 v5, v17, v5
	v_add_f32_e32 v5, v16, v5
	ds_bpermute_b32 v7, v220, v5
	v_mov_b64_e32 v[16:17], s[4:5]
	v_mad_i64_i32 v[16:17], s[0:1], v9, s0, v[16:17]
	v_mul_u32_u24_e32 v9, 0x1c00, v23
	s_waitcnt lgkmcnt(0)
	v_add_f32_e32 v5, v5, v7
	ds_bpermute_b32 v7, v221, v5
	v_lshl_add_u64 v[16:17], v[16:17], 0, v[134:135]
	v_lshlrev_b32_e32 v134, 1, v9
	v_lshl_add_u64 v[18:19], v[16:17], 0, v[134:135]
	global_store_dwordx4 v[18:19], v[24:27], off nt
	s_waitcnt lgkmcnt(0)
	v_add_f32_e32 v5, v5, v7
	ds_bpermute_b32 v7, v222, v5
	s_waitcnt lgkmcnt(0)
	v_add_f32_e32 v5, v5, v7
	ds_bpermute_b32 v7, v223, v5
	s_waitcnt lgkmcnt(0)
	v_add_f32_e32 v5, v5, v7
	v_fmamk_f32 v5, v5, 0x3c000000, v209
	v_mul_f32_e32 v7, 0x4b800000, v5
	v_cmp_gt_f32_e32 vcc, s50, v5
	s_nop 1
	v_cndmask_b32_e32 v5, v5, v7, vcc
	v_rsq_f32_e32 v5, v5
	s_nop 0
	v_mul_f32_e32 v7, 0x45800000, v5
	v_cndmask_b32_e32 v5, v5, v7, vcc
	v_mul_f32_e32 v1, v1, v5
	v_mul_f32_e32 v1, v0, v1
	v_mul_f32_e32 v3, v3, v5
	v_mul_f32_e32 v3, v2, v3
	v_cvt_pk_bf16_f32 v24, v1, v3
	v_or_b32_e32 v1, 0x800, v22
	v_mul_f32_e32 v7, v29, v5
	v_mul_f32_e32 v9, v28, v5
	v_mul_f32_e32 v11, v33, v5
	v_mul_f32_e32 v13, v32, v5
	v_mul_f32_e32 v15, v31, v5
	v_mul_f32_e32 v5, v30, v5
	v_add_u32_e32 v3, v21, v1
	v_add_u32_e32 v1, v20, v1
	v_mul_f32_e32 v7, v4, v7
	v_mul_f32_e32 v9, v6, v9
	v_mul_f32_e32 v11, v8, v11
	v_mul_f32_e32 v13, v10, v13
	v_mul_f32_e32 v15, v12, v15
	v_mul_f32_e32 v5, v14, v5
	v_cvt_pk_bf16_f32 v25, v7, v9
	v_cvt_pk_bf16_f32 v26, v11, v13
	v_cvt_pk_bf16_f32 v27, v15, v5
	ds_read_b128 v[28:31], v3
	ds_read_b128 v[32:35], v1
	s_waitcnt lgkmcnt(1)
	v_and_b32_e32 v3, 0xffff0000, v28
	s_waitcnt lgkmcnt(0)
	v_and_b32_e32 v7, 0xffff0000, v32
	v_lshlrev_b32_e32 v1, 16, v28
	v_lshlrev_b32_e32 v5, 16, v32
	v_fma_f32 v3, -v128, v7, v3
	v_and_b32_e32 v28, 0xffff0000, v29
	v_lshlrev_b32_e32 v29, 16, v29
	v_and_b32_e32 v32, 0xffff0000, v33
	v_lshlrev_b32_e32 v33, 16, v33
	v_fma_f32 v1, -v128, v5, v1
	v_mul_f32_e32 v5, v3, v3
	v_pk_fma_f32 v[28:29], v[128:129], v[32:33], v[28:29] neg_lo:[1,0,0] neg_hi:[1,0,0]
	v_fmac_f32_e32 v5, v1, v1
	v_pk_mul_f32 v[32:33], v[28:29], v[28:29]
	v_and_b32_e32 v36, 0xffff0000, v34
	v_add_f32_e32 v5, v33, v5
	v_add_f32_e32 v5, v32, v5
	v_and_b32_e32 v32, 0xffff0000, v30
	v_lshlrev_b32_e32 v33, 16, v30
	v_lshlrev_b32_e32 v37, 16, v34
	v_pk_fma_f32 v[32:33], v[128:129], v[36:37], v[32:33] neg_lo:[1,0,0] neg_hi:[1,0,0]
	v_and_b32_e32 v30, 0xffff0000, v31
	v_pk_mul_f32 v[36:37], v[32:33], v[32:33]
	v_lshlrev_b32_e32 v31, 16, v31
	v_and_b32_e32 v34, 0xffff0000, v35
	v_lshlrev_b32_e32 v35, 16, v35
	v_add_f32_e32 v5, v37, v5
	v_pk_fma_f32 v[30:31], v[128:129], v[34:35], v[30:31] neg_lo:[1,0,0] neg_hi:[1,0,0]
	v_add_f32_e32 v5, v36, v5
	v_pk_mul_f32 v[34:35], v[30:31], v[30:31]
	s_nop 0
	v_add_f32_e32 v5, v35, v5
	v_add_f32_e32 v5, v34, v5
	ds_bpermute_b32 v7, v220, v5
	v_add_co_u32_e64 v34, s[4:5], s51, v18
	s_waitcnt lgkmcnt(0)
	v_add_f32_e32 v5, v5, v7
	ds_bpermute_b32 v7, v221, v5
	v_addc_co_u32_e64 v35, s[4:5], 0, v19, s[4:5]
	global_store_dwordx4 v[34:35], v[24:27], off nt
	s_waitcnt lgkmcnt(0)
	v_add_f32_e32 v5, v5, v7
	ds_bpermute_b32 v7, v222, v5
	s_waitcnt lgkmcnt(0)
	v_add_f32_e32 v5, v5, v7
	ds_bpermute_b32 v7, v223, v5
	s_waitcnt lgkmcnt(0)
	v_add_f32_e32 v5, v5, v7
	v_fmamk_f32 v5, v5, 0x3c000000, v209
	v_mul_f32_e32 v7, 0x4b800000, v5
	v_cmp_gt_f32_e32 vcc, s50, v5
	s_nop 1
	v_cndmask_b32_e32 v5, v5, v7, vcc
	v_rsq_f32_e32 v5, v5
	s_nop 0
	v_mul_f32_e32 v7, 0x45800000, v5
	v_cndmask_b32_e32 v5, v5, v7, vcc
	v_mul_f32_e32 v1, v1, v5
	v_mul_f32_e32 v1, v0, v1
	v_mul_f32_e32 v3, v3, v5
	v_mul_f32_e32 v3, v2, v3
	v_cvt_pk_bf16_f32 v24, v1, v3
	v_or_b32_e32 v1, 0xc00, v22
	v_mul_f32_e32 v7, v29, v5
	v_mul_f32_e32 v9, v28, v5
	v_mul_f32_e32 v11, v33, v5
	v_mul_f32_e32 v13, v32, v5
	v_mul_f32_e32 v15, v31, v5
	v_mul_f32_e32 v5, v30, v5
	v_add_u32_e32 v3, v21, v1
	v_add_u32_e32 v1, v20, v1
	v_mul_f32_e32 v7, v4, v7
	v_mul_f32_e32 v9, v6, v9
	v_mul_f32_e32 v11, v8, v11
	v_mul_f32_e32 v13, v10, v13
	v_mul_f32_e32 v15, v12, v15
	v_mul_f32_e32 v5, v14, v5
	v_cvt_pk_bf16_f32 v25, v7, v9
	v_cvt_pk_bf16_f32 v26, v11, v13
	v_cvt_pk_bf16_f32 v27, v15, v5
	ds_read_b128 v[28:31], v3
	ds_read_b128 v[32:35], v1
	s_waitcnt lgkmcnt(1)
	v_and_b32_e32 v3, 0xffff0000, v28
	s_waitcnt lgkmcnt(0)
;     ...
;             for (int i = 0; i < 8; ++i) { const int row = i * 4 + (lane2 >> 4); u32x4 v = *(const u32x4*)(stg + row * 128 + ch * 8);
;                 if (mode == 2) { const u32x4 v0 = *(const u32x4*)(stash + row * 128 + ch * 8); float x0[8], x1[8]; unpack8(v0, x0); unpack8(v, x1); float ss = 0.f;
; #pragma unroll
;                     for (int e = 0; e < 8; ++e) { x0[e] = x0[e] - lam * x1[e]; ss += x0[e] * x0[e]; }
;                     ss += __shfl_xor(ss, 1); ss += __shfl_xor(ss, 2); ss += __shfl_xor(ss, 4); ss += __shfl_xor(ss, 8);
;                     const float rstd = rsqrtf(ss * (1.0f / 128) + EPS);
; #pragma unroll
;                     for (int e = 0; e < 8; ++e) x0[e] = x0[e] * rstd * gg[e];
;                     v = pack8(x0); }
;                 *(u32x4*)(Ow + (size_t)row * LDO + ch * 8) = v; }
	v_and_b32_e32 v7, 0xffff0000, v32
	v_lshlrev_b32_e32 v1, 16, v28
	v_lshlrev_b32_e32 v5, 16, v32
	v_fma_f32 v3, -v128, v7, v3
	v_and_b32_e32 v28, 0xffff0000, v29
	v_lshlrev_b32_e32 v29, 16, v29
	v_and_b32_e32 v32, 0xffff0000, v33
	v_lshlrev_b32_e32 v33, 16, v33
	v_fma_f32 v1, -v128, v5, v1
	v_mul_f32_e32 v5, v3, v3
	v_pk_fma_f32 v[28:29], v[128:129], v[32:33], v[28:29] neg_lo:[1,0,0] neg_hi:[1,0,0]
	v_fmac_f32_e32 v5, v1, v1
	v_pk_mul_f32 v[32:33], v[28:29], v[28:29]
	v_and_b32_e32 v36, 0xffff0000, v34
	v_add_f32_e32 v5, v33, v5
	v_add_f32_e32 v5, v32, v5
	v_and_b32_e32 v32, 0xffff0000, v30
	v_lshlrev_b32_e32 v33, 16, v30
	v_lshlrev_b32_e32 v37, 16, v34
	v_pk_fma_f32 v[32:33], v[128:129], v[36:37], v[32:33] neg_lo:[1,0,0] neg_hi:[1,0,0]
	v_and_b32_e32 v30, 0xffff0000, v31
	v_pk_mul_f32 v[36:37], v[32:33], v[32:33]
	v_lshlrev_b32_e32 v31, 16, v31
	v_and_b32_e32 v34, 0xffff0000, v35
	v_lshlrev_b32_e32 v35, 16, v35
	v_add_f32_e32 v5, v37, v5
	v_pk_fma_f32 v[30:31], v[128:129], v[34:35], v[30:31] neg_lo:[1,0,0] neg_hi:[1,0,0]
	v_add_f32_e32 v5, v36, v5
	v_pk_mul_f32 v[34:35], v[30:31], v[30:31]
	s_nop 0
	v_add_f32_e32 v5, v35, v5
	v_add_f32_e32 v5, v34, v5
	ds_bpermute_b32 v7, v220, v5
	v_add_co_u32_e64 v34, s[4:5], s52, v18
	s_waitcnt lgkmcnt(0)
	v_add_f32_e32 v5, v5, v7
	ds_bpermute_b32 v7, v221, v5
	v_addc_co_u32_e64 v35, s[4:5], 0, v19, s[4:5]
	global_store_dwordx4 v[34:35], v[24:27], off nt
	v_add_co_u32_e64 v18, s[4:5], s53, v18
	s_waitcnt lgkmcnt(0)
	v_add_f32_e32 v5, v5, v7
	ds_bpermute_b32 v7, v222, v5
	v_addc_co_u32_e64 v19, s[4:5], 0, v19, s[4:5]
	s_waitcnt lgkmcnt(0)
	v_add_f32_e32 v5, v5, v7
	ds_bpermute_b32 v7, v223, v5
	s_waitcnt lgkmcnt(0)
	v_add_f32_e32 v5, v5, v7
	v_fmamk_f32 v5, v5, 0x3c000000, v209
	v_mul_f32_e32 v7, 0x4b800000, v5
	v_cmp_gt_f32_e32 vcc, s50, v5
	s_nop 1
	v_cndmask_b32_e32 v5, v5, v7, vcc
	v_rsq_f32_e32 v5, v5
	s_nop 0
	v_mul_f32_e32 v7, 0x45800000, v5
	v_cndmask_b32_e32 v5, v5, v7, vcc
	v_mul_f32_e32 v1, v1, v5
	v_mul_f32_e32 v1, v0, v1
	v_mul_f32_e32 v3, v3, v5
	v_mul_f32_e32 v3, v2, v3
	v_cvt_pk_bf16_f32 v24, v1, v3
	v_or_b32_e32 v1, 0x1000, v22
	v_mul_f32_e32 v7, v29, v5
	v_mul_f32_e32 v9, v28, v5
	v_mul_f32_e32 v11, v33, v5
	v_mul_f32_e32 v13, v32, v5
	v_mul_f32_e32 v15, v31, v5
	v_mul_f32_e32 v5, v30, v5
	v_add_u32_e32 v3, v21, v1
	v_add_u32_e32 v1, v20, v1
	v_mul_f32_e32 v7, v4, v7
	v_mul_f32_e32 v9, v6, v9
	v_mul_f32_e32 v11, v8, v11
	v_mul_f32_e32 v13, v10, v13
	v_mul_f32_e32 v15, v12, v15
	v_mul_f32_e32 v5, v14, v5
	v_cvt_pk_bf16_f32 v25, v7, v9
	v_cvt_pk_bf16_f32 v26, v11, v13
	v_cvt_pk_bf16_f32 v27, v15, v5
	ds_read_b128 v[28:31], v3
	ds_read_b128 v[32:35], v1
	global_store_dwordx4 v[18:19], v[24:27], off nt
	s_waitcnt lgkmcnt(1)
	v_and_b32_e32 v3, 0xffff0000, v28
	s_waitcnt lgkmcnt(0)
	v_and_b32_e32 v7, 0xffff0000, v32
	v_lshlrev_b32_e32 v1, 16, v28
	v_lshlrev_b32_e32 v5, 16, v32
	v_fma_f32 v3, -v128, v7, v3
	v_and_b32_e32 v28, 0xffff0000, v29
	v_lshlrev_b32_e32 v29, 16, v29
	v_and_b32_e32 v32, 0xffff0000, v33
	v_lshlrev_b32_e32 v33, 16, v33
	v_fma_f32 v1, -v128, v5, v1
	v_mul_f32_e32 v5, v3, v3
	v_pk_fma_f32 v[28:29], v[128:129], v[32:33], v[28:29] neg_lo:[1,0,0] neg_hi:[1,0,0]
	v_fmac_f32_e32 v5, v1, v1
	v_pk_mul_f32 v[32:33], v[28:29], v[28:29]
	v_and_b32_e32 v36, 0xffff0000, v34
	v_add_f32_e32 v5, v33, v5
	v_add_f32_e32 v5, v32, v5
	v_and_b32_e32 v32, 0xffff0000, v30
	v_lshlrev_b32_e32 v33, 16, v30
	v_lshlrev_b32_e32 v37, 16, v34
	v_pk_fma_f32 v[32:33], v[128:129], v[36:37], v[32:33] neg_lo:[1,0,0] neg_hi:[1,0,0]
	v_and_b32_e32 v30, 0xffff0000, v31
	v_pk_mul_f32 v[36:37], v[32:33], v[32:33]
	v_lshlrev_b32_e32 v31, 16, v31
	v_and_b32_e32 v34, 0xffff0000, v35
	v_lshlrev_b32_e32 v35, 16, v35
	v_add_f32_e32 v5, v37, v5
	v_pk_fma_f32 v[30:31], v[128:129], v[34:35], v[30:31] neg_lo:[1,0,0] neg_hi:[1,0,0]
	v_add_f32_e32 v5, v36, v5
	v_pk_mul_f32 v[34:35], v[30:31], v[30:31]
	s_nop 0
	v_add_f32_e32 v5, v35, v5
	v_add_f32_e32 v5, v34, v5
	ds_bpermute_b32 v7, v220, v5
	s_waitcnt lgkmcnt(0)
	v_add_f32_e32 v5, v5, v7
	ds_bpermute_b32 v7, v221, v5
	s_waitcnt lgkmcnt(0)
	v_add_f32_e32 v5, v5, v7
	ds_bpermute_b32 v7, v222, v5
	s_waitcnt lgkmcnt(0)
	v_add_f32_e32 v5, v5, v7
	ds_bpermute_b32 v7, v223, v5
	s_waitcnt lgkmcnt(0)
	v_add_f32_e32 v5, v5, v7
	v_fmamk_f32 v5, v5, 0x3c000000, v209
	v_mul_f32_e32 v7, 0x4b800000, v5
	v_cmp_gt_f32_e32 vcc, s50, v5
	s_nop 1
	v_cndmask_b32_e32 v5, v5, v7, vcc
	v_rsq_f32_e32 v5, v5
	s_nop 0
	v_mul_f32_e32 v7, 0x45800000, v5
	v_cndmask_b32_e32 v5, v5, v7, vcc
	v_mul_f32_e32 v1, v1, v5
	v_mul_f32_e32 v1, v0, v1
	v_mul_f32_e32 v3, v3, v5
	v_mul_f32_e32 v3, v2, v3
	v_cvt_pk_bf16_f32 v24, v1, v3
	v_or_b32_e32 v1, 0x1400, v22
	v_mul_f32_e32 v7, v29, v5
	v_mul_f32_e32 v9, v28, v5
	v_mul_f32_e32 v11, v33, v5
	v_mul_f32_e32 v13, v32, v5
	v_mul_f32_e32 v15, v31, v5
	v_mul_f32_e32 v5, v30, v5
	v_add_u32_e32 v3, v21, v1
	v_add_u32_e32 v1, v20, v1
	v_mul_f32_e32 v7, v4, v7
	v_mul_f32_e32 v9, v6, v9
	v_mul_f32_e32 v11, v8, v11
	v_mul_f32_e32 v13, v10, v13
	v_mul_f32_e32 v15, v12, v15
	v_mul_f32_e32 v5, v14, v5
	v_cvt_pk_bf16_f32 v25, v7, v9
	v_cvt_pk_bf16_f32 v26, v11, v13
	v_cvt_pk_bf16_f32 v27, v15, v5
	ds_read_b128 v[28:31], v3
	ds_read_b128 v[32:35], v1
	s_waitcnt lgkmcnt(1)
	v_and_b32_e32 v3, 0xffff0000, v28
	s_waitcnt lgkmcnt(0)
;     ...
;             for (int i = 0; i < 8; ++i) { const int row = i * 4 + (lane2 >> 4); u32x4 v = *(const u32x4*)(stg + row * 128 + ch * 8);
;                 if (mode == 2) { const u32x4 v0 = *(const u32x4*)(stash + row * 128 + ch * 8); float x0[8], x1[8]; unpack8(v0, x0); unpack8(v, x1); float ss = 0.f;
; #pragma unroll
;                     for (int e = 0; e < 8; ++e) { x0[e] = x0[e] - lam * x1[e]; ss += x0[e] * x0[e]; }
;                     ss += __shfl_xor(ss, 1); ss += __shfl_xor(ss, 2); ss += __shfl_xor(ss, 4); ss += __shfl_xor(ss, 8);
;                     const float rstd = rsqrtf(ss * (1.0f / 128) + EPS);
; #pragma unroll
;                     for (int e = 0; e < 8; ++e) x0[e] = x0[e] * rstd * gg[e];
;                     v = pack8(x0); }
;                 *(u32x4*)(Ow + (size_t)row * LDO + ch * 8) = v; }
	v_and_b32_e32 v7, 0xffff0000, v32
	v_lshlrev_b32_e32 v1, 16, v28
	v_lshlrev_b32_e32 v5, 16, v32
	v_fma_f32 v3, -v128, v7, v3
	v_and_b32_e32 v18, 0xffff0000, v29
	v_lshlrev_b32_e32 v19, 16, v29
	v_and_b32_e32 v28, 0xffff0000, v33
	v_lshlrev_b32_e32 v29, 16, v33
	v_fma_f32 v1, -v128, v5, v1
	v_mul_f32_e32 v5, v3, v3
	v_pk_fma_f32 v[18:19], v[128:129], v[28:29], v[18:19] neg_lo:[1,0,0] neg_hi:[1,0,0]
	v_fmac_f32_e32 v5, v1, v1
	v_pk_mul_f32 v[28:29], v[18:19], v[18:19]
	v_and_b32_e32 v32, 0xffff0000, v34
	v_add_f32_e32 v5, v29, v5
	v_add_f32_e32 v5, v28, v5
	v_and_b32_e32 v28, 0xffff0000, v30
	v_lshlrev_b32_e32 v29, 16, v30
	v_lshlrev_b32_e32 v33, 16, v34
	v_pk_fma_f32 v[28:29], v[128:129], v[32:33], v[28:29] neg_lo:[1,0,0] neg_hi:[1,0,0]
	v_and_b32_e32 v30, 0xffff0000, v31
	v_pk_mul_f32 v[32:33], v[28:29], v[28:29]
	v_lshlrev_b32_e32 v31, 16, v31
	v_add_f32_e32 v5, v33, v5
	v_add_f32_e32 v5, v32, v5
	v_and_b32_e32 v32, 0xffff0000, v35
	v_lshlrev_b32_e32 v33, 16, v35
	v_pk_fma_f32 v[30:31], v[128:129], v[32:33], v[30:31] neg_lo:[1,0,0] neg_hi:[1,0,0]
	s_nop 0
	v_pk_mul_f32 v[32:33], v[30:31], v[30:31]
	s_nop 0
	v_add_f32_e32 v5, v33, v5
	v_add_f32_e32 v5, v32, v5
	ds_bpermute_b32 v7, v220, v5
	v_add_u32_e32 v32, 0x38000, v134
	v_mov_b32_e32 v33, v135
	v_lshl_add_u64 v[32:33], v[16:17], 0, v[32:33]
	global_store_dwordx4 v[32:33], v[24:27], off nt
	s_waitcnt lgkmcnt(0)
	v_add_f32_e32 v5, v5, v7
	ds_bpermute_b32 v7, v221, v5
	s_waitcnt lgkmcnt(0)
	v_add_f32_e32 v5, v5, v7
	ds_bpermute_b32 v7, v222, v5
	s_waitcnt lgkmcnt(0)
	v_add_f32_e32 v5, v5, v7
	ds_bpermute_b32 v7, v223, v5
	s_waitcnt lgkmcnt(0)
	v_add_f32_e32 v5, v5, v7
	v_fmamk_f32 v5, v5, 0x3c000000, v209
	v_mul_f32_e32 v7, 0x4b800000, v5
	v_cmp_gt_f32_e32 vcc, s50, v5
	s_nop 1
	v_cndmask_b32_e32 v5, v5, v7, vcc
	v_rsq_f32_e32 v5, v5
	s_nop 0
	v_mul_f32_e32 v7, 0x45800000, v5
	v_cndmask_b32_e32 v5, v5, v7, vcc
	v_mul_f32_e32 v1, v1, v5
	v_mul_f32_e32 v1, v0, v1
	v_mul_f32_e32 v3, v3, v5
	v_mul_f32_e32 v3, v2, v3
	v_cvt_pk_bf16_f32 v24, v1, v3
	v_or_b32_e32 v1, 0x1800, v22
	v_mul_f32_e32 v7, v19, v5
	v_mul_f32_e32 v9, v18, v5
	v_mul_f32_e32 v11, v29, v5
	v_mul_f32_e32 v13, v28, v5
	v_mul_f32_e32 v15, v31, v5
	v_mul_f32_e32 v5, v30, v5
	v_add_u32_e32 v3, v21, v1
	v_add_u32_e32 v1, v20, v1
	v_mul_f32_e32 v7, v4, v7
	v_mul_f32_e32 v9, v6, v9
	v_mul_f32_e32 v11, v8, v11
	v_mul_f32_e32 v13, v10, v13
	v_mul_f32_e32 v15, v12, v15
	v_mul_f32_e32 v5, v14, v5
	v_cvt_pk_bf16_f32 v25, v7, v9
	v_cvt_pk_bf16_f32 v26, v11, v13
	v_cvt_pk_bf16_f32 v27, v15, v5
	ds_read_b128 v[28:31], v3
	ds_read_b128 v[32:35], v1
	s_waitcnt lgkmcnt(1)
	v_and_b32_e32 v3, 0xffff0000, v28
	s_waitcnt lgkmcnt(0)
	v_and_b32_e32 v7, 0xffff0000, v32
	v_lshlrev_b32_e32 v1, 16, v28
	v_lshlrev_b32_e32 v5, 16, v32
	v_fma_f32 v3, -v128, v7, v3
	v_and_b32_e32 v18, 0xffff0000, v29
	v_lshlrev_b32_e32 v19, 16, v29
	v_and_b32_e32 v28, 0xffff0000, v33
	v_lshlrev_b32_e32 v29, 16, v33
	v_fma_f32 v1, -v128, v5, v1
	v_mul_f32_e32 v5, v3, v3
	v_pk_fma_f32 v[18:19], v[128:129], v[28:29], v[18:19] neg_lo:[1,0,0] neg_hi:[1,0,0]
	v_fmac_f32_e32 v5, v1, v1
	v_pk_mul_f32 v[28:29], v[18:19], v[18:19]
	v_and_b32_e32 v32, 0xffff0000, v34
	v_add_f32_e32 v5, v29, v5
	v_add_f32_e32 v5, v28, v5
	v_and_b32_e32 v28, 0xffff0000, v30
	v_lshlrev_b32_e32 v29, 16, v30
	v_lshlrev_b32_e32 v33, 16, v34
	v_pk_fma_f32 v[28:29], v[128:129], v[32:33], v[28:29] neg_lo:[1,0,0] neg_hi:[1,0,0]
	v_and_b32_e32 v30, 0xffff0000, v31
	v_pk_mul_f32 v[32:33], v[28:29], v[28:29]
	v_lshlrev_b32_e32 v31, 16, v31
	v_add_f32_e32 v5, v33, v5
	v_add_f32_e32 v5, v32, v5
	v_and_b32_e32 v32, 0xffff0000, v35
	v_lshlrev_b32_e32 v33, 16, v35
	v_pk_fma_f32 v[30:31], v[128:129], v[32:33], v[30:31] neg_lo:[1,0,0] neg_hi:[1,0,0]
	s_nop 0
	v_pk_mul_f32 v[32:33], v[30:31], v[30:31]
	s_nop 0
	v_add_f32_e32 v5, v33, v5
	v_add_f32_e32 v5, v32, v5
	ds_bpermute_b32 v7, v220, v5
	v_add_u32_e32 v32, 0x46000, v134
	v_mov_b32_e32 v33, v135
	v_lshl_add_u64 v[32:33], v[16:17], 0, v[32:33]
	global_store_dwordx4 v[32:33], v[24:27], off nt
	s_waitcnt lgkmcnt(0)
	v_add_f32_e32 v5, v5, v7
	ds_bpermute_b32 v7, v221, v5
	s_waitcnt lgkmcnt(0)
	v_add_f32_e32 v5, v5, v7
	ds_bpermute_b32 v7, v222, v5
	s_waitcnt lgkmcnt(0)
	v_add_f32_e32 v5, v5, v7
	ds_bpermute_b32 v7, v223, v5
	s_waitcnt lgkmcnt(0)
; __device__ __forceinline__ int v_rd_base(int lane) { return ((lane & 3) << 3) | (((lane >> 2) & 3) << 6) | (((lane >> 4) & 1) << 5) | (((lane >> 5) & 1) << 8); }
;     ...
;         const bf16_t* Qw = Qb + (size_t)(wid * QBLK + r32) * LDQ + hi * 8;
; #pragma unroll
;         for (int d0 = 0; d0 < NREG; ++d0) qr[d0] = *(const bf16x8*)(Qw + d0 * 16);
; #pragma unroll
;         for (int d0 = NREG; d0 < ND0; ++d0) *(bf16x8*)(qs + (d0 - NREG) * 1024) = *(const bf16x8*)(Qw + d0 * 16);
;     }
;     const int widu = __builtin_amdgcn_readfirstlane(wid);
;     const int vb0 = (int)(uintptr_t)V_lds + v_rd_base(lane);
;     unsigned ksrc[2], vsrc[2];
; #pragma unroll
;     for (int i = 0; i < 2; ++i) {
;         if (DQK == 128) { const int j = wid * 2 + i, row = 4 * j + (lane >> 4), c = (lane & 15) ^ (row & 15); ksrc[i] = (unsigned)(row * LDK + c * 8) * 2u; }
;         else { const int row = 8 * wid + (lane >> 3), c = (lane & 7) ^ ((row >> 1) & 7); ksrc[i] = (unsigned)(row * LDK + c * 8) * 2u; }
;         const int j = wid * 2 + i, st = 2 * j + (lane >> 5), kk = (st >> 2) * 8 + ((lane & 31) >> 2), c = (st & 3) * 32 + (lane & 3) * 8;
;         const int k = (kk & ~0xC) | ((kk & 4) << 1) | ((kk & 8) >> 1);
;         vsrc[i] = (unsigned)(k * LDK + c) * 2u;
;     }
;     constexpr size_t TILEB = (size_t)KVBLK * LDK * 2;
;     const unsigned lds0 = (unsigned)(uintptr_t)lds;
;     ...
;     f32x16 pA0, pA1, pB0, pB1; bf16x8 pa0, pa1, pa2, pa3;
;     DMA_K(0, 0); WBAR0();
;     if (__builtin_amdgcn_readfirstlane(tid_) >= 256) __builtin_amdgcn_s_setprio(1);
;     ...
;             for (int i = 0; i < 8; ++i) { const int row = i * 4 + (lane2 >> 4); u32x4 v = *(const u32x4*)(stg + row * 128 + ch * 8);
;                 if (mode == 2) { const u32x4 v0 = *(const u32x4*)(stash + row * 128 + ch * 8); float x0[8], x1[8]; unpack8(v0, x0); unpack8(v, x1); float ss = 0.f;
; #pragma unroll
;                     for (int e = 0; e < 8; ++e) { x0[e] = x0[e] - lam * x1[e]; ss += x0[e] * x0[e]; }
;                     ss += __shfl_xor(ss, 1); ss += __shfl_xor(ss, 2); ss += __shfl_xor(ss, 4); ss += __shfl_xor(ss, 8);
;                     const float rstd = rsqrtf(ss * (1.0f / 128) + EPS);
; #pragma unroll
;                     for (int e = 0; e < 8; ++e) x0[e] = x0[e] * rstd * gg[e];
;                     v = pack8(x0); }
;                 *(u32x4*)(Ow + (size_t)row * LDO + ch * 8) = v; }
	v_add_f32_e32 v5, v5, v7
	v_fmamk_f32 v5, v5, 0x3c000000, v209
	v_mul_f32_e32 v7, 0x4b800000, v5
	v_cmp_gt_f32_e32 vcc, s50, v5
	s_nop 1
	v_cndmask_b32_e32 v5, v5, v7, vcc
	v_rsq_f32_e32 v5, v5
	s_nop 0
	v_mul_f32_e32 v7, 0x45800000, v5
	v_cndmask_b32_e32 v5, v5, v7, vcc
	v_mul_f32_e32 v1, v1, v5
	v_mul_f32_e32 v1, v0, v1
	v_mul_f32_e32 v3, v3, v5
	v_mul_f32_e32 v3, v2, v3
	v_cvt_pk_bf16_f32 v24, v1, v3
	v_or_b32_e32 v1, 0x1c00, v22
	v_mul_f32_e32 v7, v19, v5
	v_mul_f32_e32 v9, v18, v5
	v_mul_f32_e32 v11, v29, v5
	v_mul_f32_e32 v13, v28, v5
	v_mul_f32_e32 v15, v31, v5
	v_mul_f32_e32 v5, v30, v5
	v_add_u32_e32 v3, v21, v1
	v_add_u32_e32 v1, v20, v1
	v_mul_f32_e32 v7, v4, v7
	v_mul_f32_e32 v9, v6, v9
	v_mul_f32_e32 v11, v8, v11
	v_mul_f32_e32 v13, v10, v13
	v_mul_f32_e32 v15, v12, v15
	v_mul_f32_e32 v5, v14, v5
	v_cvt_pk_bf16_f32 v25, v7, v9
	v_cvt_pk_bf16_f32 v26, v11, v13
	v_cvt_pk_bf16_f32 v27, v15, v5
	ds_read_b128 v[28:31], v3
	ds_read_b128 v[18:21], v1
	s_waitcnt lgkmcnt(1)
	v_and_b32_e32 v3, 0xffff0000, v28
	s_waitcnt lgkmcnt(0)
	v_and_b32_e32 v7, 0xffff0000, v18
	v_lshlrev_b32_e32 v1, 16, v28
	v_lshlrev_b32_e32 v5, 16, v18
	v_fma_f32 v3, -v128, v7, v3
	v_and_b32_e32 v22, 0xffff0000, v29
	v_lshlrev_b32_e32 v23, 16, v29
	v_and_b32_e32 v18, 0xffff0000, v19
	v_lshlrev_b32_e32 v19, 16, v19
	v_fma_f32 v1, -v128, v5, v1
	v_mul_f32_e32 v5, v3, v3
	v_pk_fma_f32 v[18:19], v[128:129], v[18:19], v[22:23] neg_lo:[1,0,0] neg_hi:[1,0,0]
	v_fmac_f32_e32 v5, v1, v1
	v_pk_mul_f32 v[22:23], v[18:19], v[18:19]
	v_and_b32_e32 v28, 0xffff0000, v20
	v_add_f32_e32 v5, v23, v5
	v_add_f32_e32 v5, v22, v5
	v_and_b32_e32 v22, 0xffff0000, v30
	v_lshlrev_b32_e32 v23, 16, v30
	v_lshlrev_b32_e32 v29, 16, v20
	v_pk_fma_f32 v[22:23], v[128:129], v[28:29], v[22:23] neg_lo:[1,0,0] neg_hi:[1,0,0]
	v_and_b32_e32 v20, 0xffff0000, v21
	v_pk_mul_f32 v[28:29], v[22:23], v[22:23]
	v_lshlrev_b32_e32 v21, 16, v21
	v_add_f32_e32 v5, v29, v5
	v_add_f32_e32 v5, v28, v5
	v_and_b32_e32 v28, 0xffff0000, v31
	v_lshlrev_b32_e32 v29, 16, v31
	v_pk_fma_f32 v[20:21], v[128:129], v[20:21], v[28:29] neg_lo:[1,0,0] neg_hi:[1,0,0]
	s_nop 0
	v_pk_mul_f32 v[28:29], v[20:21], v[20:21]
	s_nop 0
	v_add_f32_e32 v5, v29, v5
	v_add_f32_e32 v5, v28, v5
	ds_bpermute_b32 v7, v220, v5
	v_add_u32_e32 v28, 0x54000, v134
	v_mov_b32_e32 v29, v135
	v_lshl_add_u64 v[28:29], v[16:17], 0, v[28:29]
	v_add_u32_e32 v134, 0x62000, v134
	s_waitcnt lgkmcnt(0)
	v_add_f32_e32 v5, v5, v7
	ds_bpermute_b32 v7, v221, v5
	global_store_dwordx4 v[28:29], v[24:27], off nt
	s_waitcnt lgkmcnt(0)
	v_add_f32_e32 v5, v5, v7
	ds_bpermute_b32 v7, v222, v5
	s_waitcnt lgkmcnt(0)
	v_add_f32_e32 v5, v5, v7
	ds_bpermute_b32 v7, v223, v5
	s_waitcnt lgkmcnt(0)
	v_add_f32_e32 v5, v5, v7
	v_fmamk_f32 v5, v5, 0x3c000000, v209
	v_mul_f32_e32 v7, 0x4b800000, v5
	v_cmp_gt_f32_e32 vcc, s50, v5
	s_nop 1
	v_cndmask_b32_e32 v5, v5, v7, vcc
	v_rsq_f32_e32 v5, v5
	s_nop 0
	v_mul_f32_e32 v7, 0x45800000, v5
	v_cndmask_b32_e32 v5, v5, v7, vcc
	v_mul_f32_e32 v1, v1, v5
	v_mul_f32_e32 v0, v0, v1
	v_mul_f32_e32 v1, v3, v5
	v_mul_f32_e32 v1, v2, v1
	v_mul_f32_e32 v2, v19, v5
	v_mul_f32_e32 v3, v18, v5
	v_mul_f32_e32 v2, v4, v2
	v_mul_f32_e32 v3, v6, v3
	v_mul_f32_e32 v4, v23, v5
	v_mul_f32_e32 v6, v22, v5
	v_mul_f32_e32 v7, v21, v5
	v_mul_f32_e32 v5, v20, v5
	v_mul_f32_e32 v4, v8, v4
	v_mul_f32_e32 v5, v14, v5
	v_mul_f32_e32 v6, v10, v6
	v_mul_f32_e32 v7, v12, v7
	v_cvt_pk_bf16_f32 v0, v0, v1
	v_cvt_pk_bf16_f32 v1, v2, v3
	v_cvt_pk_bf16_f32 v2, v4, v6
	v_cvt_pk_bf16_f32 v3, v7, v5
	v_lshl_add_u64 v[4:5], v[16:17], 0, v[134:135]
	global_store_dwordx4 v[4:5], v[0:3], off nt
	s_nop 0
	s_barrier
	s_cbranch_scc1 .LBB0_570
.LBB0_558:
	s_ashr_i32 s0, s54, 7
	s_lshl_b32 s4, s54, 8
	s_lshl_b32 s1, s0, 12
	s_and_b32 s4, s4, 0xf00
	s_or_b32 s1, s1, s4
	s_mul_hi_i32 s4, s1, 0x3800
	s_mulk_i32 s1, 0x3800
	s_add_u32 s1, s12, s1
	s_addc_u32 s4, s13, s4
	s_lshl_b32 s5, s54, 3
	s_and_b32 s5, s5, 0x380
	s_lshl_b32 s48, s5, 1
	s_add_u32 s1, s1, s48
	s_addc_u32 s5, s4, 0
	s_add_u32 s4, s1, 0x1000
	s_addc_u32 s5, s5, 0
	v_lshl_add_u64 v[0:1], v[130:131], 1, s[4:5]
	v_lshl_add_u64 v[144:145], v[0:1], 0, v[138:139]
	global_load_dwordx4 v[108:111], v[144:145], off nt
	global_load_dwordx4 v[104:107], v[144:145], off offset:32 nt
	global_load_dwordx4 v[100:103], v[144:145], off offset:64 nt
	global_load_dwordx4 v[96:99], v[144:145], off offset:96 nt
	s_mul_i32 s47, s0, 0x1980000
	s_mul_hi_i32 s46, s0, 0x1980000
	s_add_u32 s72, s10, s47
	s_addc_u32 s74, s11, s46
	s_add_u32 s0, s72, s48
	s_addc_u32 s1, s74, 0
	s_add_u32 s76, s0, 0x800
	v_readfirstlane_b32 s49, v202
	s_addc_u32 s77, s1, 0
	s_lshl_b32 s73, s49, 10
	s_cmp_lg_u32 0, -1
	s_cselect_b32 s55, 0, 0
	s_add_i32 s55, s55, s73
	v_lshl_add_u64 v[142:143], s[76:77], 0, v[136:137]
	s_add_i32 s55, s55, 0x8000
	s_mov_b32 s75, m0
	s_mov_b32 m0, s55
	s_nop 0
	global_load_lds_dwordx4 v[142:143], off
	s_mov_b32 m0, s75
	s_waitcnt vmcnt(0)
	s_nop 0
	v_readfirstlane_b32 s75, v218
	s_cmpk_lt_i32 s75, 0x100
	s_barrier
	s_cbranch_scc1 .LBB0_560
	s_setprio 1

; #define SBAR() __builtin_amdgcn_sched_barrier(0)
; #define DMA_K(t, buf) do { const char* kb_ = (const char*)Kh + (size_t)(t) * TILEB; \
;         glds16(kb_ + ksrc[0], (unsigned)__builtin_amdgcn_readfirstlane(lds0 + OFF_K + (buf) * SHM_K + (DQK == 128 ? widu * 2048 : widu * 1024))); \
;         if (DQK == 128) glds16(kb_ + ksrc[1], (unsigned)__builtin_amdgcn_readfirstlane(lds0 + OFF_K + (buf) * SHM_K + widu * 2048 + 1024)); } while (0)
; #define DMA_V(t, buf) do { const char* vb_ = (const char*)Vh + (size_t)(t) * TILEB; \
;         glds16(vb_ + vsrc[0], (unsigned)__builtin_amdgcn_readfirstlane(lds0 + (buf) * SHM_V + widu * 2048)); \
;         glds16(vb_ + vsrc[1], (unsigned)__builtin_amdgcn_readfirstlane(lds0 + (buf) * SHM_V + widu * 2048 + 1024)); } while (0)
; #define WBAR0() do { asm volatile("s_waitcnt vmcnt(0)" ::: "memory"); __syncthreads(); } while (0)
; #define EXPH(P) do { _Pragma("unroll") for (int r = 0; r < 16; ++r) P[r] = __builtin_amdgcn_exp2f(P[r]); } while (0)
;     ...
;     for (int k = 1; k + 1 < NT; k += 2) {
;         DMA_K(k + 1, 0); DMA_V(k, 1); SBAR();
;         if (isY) { EXPH(pA0); }
;         SBAR(); qkt_mix<DQK, NREG>(pB0, pB1, K_lds + SHM_K, qr, qs, r32, hi);
;         finishSM<true>(pA0, pA1, dummy_a, l_reg, pa0, pa1, pa2, pa3); SBAR();
;         pv_d0(o, vb0, pa0, pa1, pa2, pa3);
;         if (!isY) { EXPH(pB0); }
;         WBAR0();
.LBB0_561:
	v_lshl_add_u64 v[80:81], v[152:153], 0, s[22:23]
	s_mov_b32 s0, m0
	s_mov_b32 m0, s55
	s_nop 0
	global_load_lds_dwordx4 v[80:81], off
	s_mov_b32 m0, s0
	s_cmp_lg_u32 0, -1
	s_cselect_b32 s0, 0, 0
	s_add_i32 s0, s0, s73
	v_lshl_add_u64 v[186:187], s[48:49], 0, v[132:133]
	s_add_i32 s1, s0, 0x4000
	s_mov_b32 s77, m0
	s_mov_b32 m0, s1
	s_nop 0
	global_load_lds_dwordx4 v[186:187], off
	s_mov_b32 m0, s77
	v_lshl_add_u64 v[80:81], v[186:187], 0, s[20:21]
	s_addk_i32 s0, 0x4400
	s_mov_b32 s1, m0
	s_mov_b32 m0, s0
	s_nop 0
	global_load_lds_dwordx4 v[80:81], off
	s_mov_b32 m0, s1
	ds_read_b128 v[80:83], v205 offset:40960
	ds_read_b128 v[124:127], v205 offset:45056
	ds_read_b128 v[112:115], v206 offset:40960
	ds_read_b128 v[120:123], v206 offset:45056
	s_waitcnt lgkmcnt(3)
	v_mfma_f32_32x32x16_bf16 v[80:95], v[80:83], v[108:111], 0
	s_waitcnt lgkmcnt(1)
	v_mfma_f32_32x32x16_bf16 v[80:95], v[112:115], v[104:107], v[80:95]
	ds_read_b128 v[112:115], v207 offset:40960
	ds_read_b128 v[116:119], v207 offset:45056
	s_waitcnt lgkmcnt(1)
	v_mfma_f32_32x32x16_bf16 v[80:95], v[112:115], v[100:103], v[80:95]
	ds_read_b128 v[172:175], v208 offset:40960
	ds_read_b128 v[112:115], v208 offset:45056
	s_waitcnt lgkmcnt(1)
	v_mfma_f32_32x32x16_bf16 v[80:95], v[172:175], v[96:99], v[80:95]
	v_exp_f32_e32 v199, v64
	v_exp_f32_e32 v197, v65
	v_exp_f32_e32 v198, v66
	v_exp_f32_e32 v196, v67
	v_exp_f32_e32 v67, v69
	v_exp_f32_e32 v66, v71
	v_exp_f32_e32 v65, v72
	v_exp_f32_e32 v64, v74
	v_exp_f32_e32 v195, v68
	v_exp_f32_e32 v194, v70
	v_exp_f32_e32 v193, v73
	v_exp_f32_e32 v192, v75
	v_exp_f32_e32 v191, v76
	v_exp_f32_e32 v189, v77
	v_exp_f32_e32 v190, v78
	v_exp_f32_e32 v188, v79
	v_cvt_pk_bf16_f32 v68, v171, v169
	v_cvt_pk_bf16_f32 v69, v170, v168
	v_cvt_pk_bf16_f32 v70, v167, v165
	v_cvt_pk_bf16_f32 v71, v166, v164
	v_cvt_pk_bf16_f32 v72, v163, v161
	v_cvt_pk_bf16_f32 v73, v162, v160
	v_cvt_pk_bf16_f32 v74, v159, v157
	v_cvt_pk_bf16_f32 v75, v158, v156
	v_cvt_pk_bf16_f32 v76, v199, v197
	v_cvt_pk_bf16_f32 v77, v198, v196
	v_cvt_pk_bf16_f32 v78, v195, v67
	v_cvt_pk_bf16_f32 v79, v194, v66
	s_nop 0
	v_permlane32_swap_b32_e32 v68, v70
	v_permlane32_swap_b32_e32 v69, v71
	v_permlane32_swap_b32_e32 v72, v74
	v_permlane32_swap_b32_e32 v73, v75
	v_permlane32_swap_b32_e32 v76, v78
	v_permlane32_swap_b32_e32 v77, v79
	v_cvt_pk_bf16_f32 v210, v65, v193
	v_cvt_pk_bf16_f32 v211, v64, v192
	v_cvt_pk_bf16_f32 v212, v191, v189
	v_cvt_pk_bf16_f32 v213, v190, v188
	s_nop 0
	v_permlane32_swap_b32_e32 v210, v212
	v_permlane32_swap_b32_e32 v211, v213
	ds_read_b64_tr_b16 v[172:173], v203 offset:0
	ds_read_b64_tr_b16 v[174:175], v203 offset:0x800
	ds_read_b64_tr_b16 v[176:177], v203 offset:0x1000
	ds_read_b64_tr_b16 v[178:179], v203 offset:0x1800
	ds_read_b64_tr_b16 v[180:181], v203 offset:0x2000
	ds_read_b64_tr_b16 v[182:183], v203 offset:0x2800
	ds_read_b64_tr_b16 v[214:215], v203 offset:0x3000
	ds_read_b64_tr_b16 v[216:217], v203 offset:0x3800
	s_waitcnt lgkmcnt(0)
	s_nop 0
	v_mfma_f32_32x32x16_bf16 v[0:15], v[68:71], v[172:175], v[0:15]
	ds_read_b64_tr_b16 v[172:173], v203 offset:0x200
	ds_read_b64_tr_b16 v[174:175], v203 offset:0xa00
	v_mfma_f32_32x32x16_bf16 v[0:15], v[72:75], v[176:179], v[0:15]
	ds_read_b64_tr_b16 v[176:177], v203 offset:0x1200
	ds_read_b64_tr_b16 v[178:179], v203 offset:0x1a00
	v_mfma_f32_32x32x16_bf16 v[0:15], v[76:79], v[180:183], v[0:15]
	ds_read_b64_tr_b16 v[180:181], v203 offset:0x2200
	ds_read_b64_tr_b16 v[182:183], v203 offset:0x2a00
	ds_read_b64_tr_b16 v[224:225], v203 offset:0x3200
	ds_read_b64_tr_b16 v[226:227], v203 offset:0x3a00
	s_waitcnt lgkmcnt(0)
	v_mfma_f32_32x32x16_bf16 v[0:15], v[210:213], v[214:217], v[0:15]
	v_mfma_f32_32x32x16_bf16 v[16:31], v[68:71], v[172:175], v[16:31]
	ds_read_b64_tr_b16 v[172:173], v203 offset:0x400
	ds_read_b64_tr_b16 v[174:175], v203 offset:0xc00
	v_mfma_f32_32x32x16_bf16 v[16:31], v[72:75], v[176:179], v[16:31]
	ds_read_b64_tr_b16 v[176:177], v203 offset:0x1400
	ds_read_b64_tr_b16 v[178:179], v203 offset:0x1c00
	v_mfma_f32_32x32x16_bf16 v[16:31], v[76:79], v[180:183], v[16:31]
	ds_read_b64_tr_b16 v[180:181], v203 offset:0x2400
	ds_read_b64_tr_b16 v[182:183], v203 offset:0x2c00
	ds_read_b64_tr_b16 v[214:215], v203 offset:0x3400
	ds_read_b64_tr_b16 v[216:217], v203 offset:0x3c00
	s_waitcnt lgkmcnt(0)
	v_mfma_f32_32x32x16_bf16 v[16:31], v[210:213], v[224:227], v[16:31]
	v_mfma_f32_32x32x16_bf16 v[32:47], v[68:71], v[172:175], v[32:47]
	ds_read_b64_tr_b16 v[172:173], v203 offset:0x600
	ds_read_b64_tr_b16 v[174:175], v203 offset:0xe00
	v_mfma_f32_32x32x16_bf16 v[32:47], v[72:75], v[176:179], v[32:47]
	ds_read_b64_tr_b16 v[176:177], v203 offset:0x1600
	ds_read_b64_tr_b16 v[178:179], v203 offset:0x1e00
	ds_read_b64_tr_b16 v[224:225], v203 offset:0x2600
	ds_read_b64_tr_b16 v[226:227], v203 offset:0x2e00
	ds_read_b64_tr_b16 v[228:229], v203 offset:0x3600
	ds_read_b64_tr_b16 v[230:231], v203 offset:0x3e00
	s_waitcnt lgkmcnt(0)
	v_mfma_f32_32x32x16_bf16 v[32:47], v[76:79], v[180:183], v[32:47]
	v_mfma_f32_32x32x16_bf16 v[32:47], v[210:213], v[214:217], v[32:47]
	v_mfma_f32_32x32x16_bf16 v[48:63], v[68:71], v[172:175], v[48:63]
	v_exp_f32_e32 v180, v86
	v_exp_f32_e32 v175, v89
	v_exp_f32_e32 v185, v80
	v_exp_f32_e32 v183, v81
	v_exp_f32_e32 v184, v82
	v_exp_f32_e32 v182, v83
	v_add_f32_e32 v80, v170, v198
	v_add_f32_e32 v81, v171, v199
	v_mfma_f32_32x32x16_bf16 v[48:63], v[72:75], v[176:179], v[48:63]
	v_exp_f32_e32 v178, v87
	v_exp_f32_e32 v177, v88
	v_add_f32_e32 v86, v164, v66
	v_add_f32_e32 v87, v165, v67
	v_add_f32_e32 v88, v162, v64
	v_add_f32_e32 v89, v163, v65
	v_add_f32_e32 v82, v168, v196
	v_add_f32_e32 v83, v169, v197
	v_exp_f32_e32 v181, v84
	v_exp_f32_e32 v179, v85
	v_mfma_f32_32x32x16_bf16 v[48:63], v[76:79], v[224:227], v[48:63]
	v_add_f32_e64 v84, v166, v194
	v_add_f32_e64 v85, v167, v195
	v_exp_f32_e32 v176, v90
	v_exp_f32_e32 v174, v91
	v_add_f32_e32 v90, v160, v192
	v_add_f32_e32 v91, v161, v193
	v_add_f32_e32 v80, v84, v80
	v_add_f32_e32 v81, v85, v81
	v_mfma_f32_32x32x16_bf16 v[64:79], v[124:127], v[108:111], 0
	v_add_f32_e64 v82, v86, v82
	v_add_f32_e64 v83, v87, v83
	v_exp_f32_e32 v173, v92
	v_exp_f32_e32 v155, v93
	v_exp_f32_e32 v172, v94
	v_exp_f32_e32 v154, v95
	v_add_f32_e32 v92, v158, v190
	v_add_f32_e32 v93, v159, v191
	v_add_f32_e32 v94, v156, v188
	v_add_f32_e32 v95, v157, v189
	v_mfma_f32_32x32x16_bf16 v[64:79], v[120:123], v[104:107], v[64:79]
	v_add_f32_e64 v80, v88, v80
	v_add_f32_e64 v81, v89, v81
	v_add_f32_e64 v82, v90, v82
	v_add_f32_e64 v83, v91, v83
	v_add_f32_e64 v80, v92, v80
	v_add_f32_e64 v81, v93, v81
	v_add_f32_e32 v82, v94, v82
	v_add_f32_e32 v83, v95, v83
	s_waitcnt vmcnt(0)
	s_waitcnt lgkmcnt(0)
	v_add_f32_e32 v80, v82, v80
	v_add_f32_e32 v81, v83, v81
	v_mfma_f32_32x32x16_bf16 v[64:79], v[116:119], v[100:103], v[64:79]
	s_barrier
; #define SBAR() __builtin_amdgcn_sched_barrier(0)
; #define DMA_K(t, buf) do { const char* kb_ = (const char*)Kh + (size_t)(t) * TILEB; \
;         glds16(kb_ + ksrc[0], (unsigned)__builtin_amdgcn_readfirstlane(lds0 + OFF_K + (buf) * SHM_K + (DQK == 128 ? widu * 2048 : widu * 1024))); \
;         if (DQK == 128) glds16(kb_ + ksrc[1], (unsigned)__builtin_amdgcn_readfirstlane(lds0 + OFF_K + (buf) * SHM_K + widu * 2048 + 1024)); } while (0)
; #define DMA_V(t, buf) do { const char* vb_ = (const char*)Vh + (size_t)(t) * TILEB; \
;         glds16(vb_ + vsrc[0], (unsigned)__builtin_amdgcn_readfirstlane(lds0 + (buf) * SHM_V + widu * 2048)); \
;         glds16(vb_ + vsrc[1], (unsigned)__builtin_amdgcn_readfirstlane(lds0 + (buf) * SHM_V + widu * 2048 + 1024)); } while (0)
; #define EXPH(P) do { _Pragma("unroll") for (int r = 0; r < 16; ++r) P[r] = __builtin_amdgcn_exp2f(P[r]); } while (0)
;     ...
;         DMA_K(k + 2, 1); DMA_V(k + 1, 0); SBAR();
;         if (isY) { EXPH(pB0); }
;         SBAR(); qkt_mix<DQK, NREG>(pA0, pA1, K_lds, qr, qs, r32, hi);
;         finishSM<true>(pB0, pB1, dummy_a, l_reg, pa0, pa1, pa2, pa3); SBAR();
;         pv_d0(o, vb0 + SHM_V, pa0, pa1, pa2, pa3);
;         if (!isY) { EXPH(pA0); }
	s_mov_b32 s0, m0
	s_mov_b32 m0, s74
	s_nop 0
	global_load_lds_dwordx4 v[152:153], off
	s_mov_b32 m0, s0
	v_add_f32_e32 v141, v80, v81
	v_lshl_add_u64 v[80:81], v[186:187], 0, s[6:7]
	s_mov_b32 s0, m0
	s_mov_b32 m0, s75
	s_nop 0
	global_load_lds_dwordx4 v[80:81], off
	s_mov_b32 m0, s0
	v_lshl_add_u64 v[80:81], v[186:187], 0, s[26:27]
	v_mfma_f32_32x32x16_bf16 v[48:63], v[210:213], v[228:231], v[48:63]
	s_mov_b32 s0, m0
	s_mov_b32 m0, s76
	s_nop 0
	global_load_lds_dwordx4 v[80:81], off
	s_mov_b32 m0, s0
	v_mfma_f32_32x32x16_bf16 v[64:79], v[112:115], v[96:99], v[64:79]
	ds_read_b128 v[80:83], v205 offset:32768
	ds_read_b128 v[156:159], v205 offset:36864
	ds_read_b128 v[112:115], v206 offset:32768
	ds_read_b128 v[124:127], v206 offset:36864
	s_waitcnt lgkmcnt(3)
	v_mfma_f32_32x32x16_bf16 v[80:95], v[80:83], v[108:111], 0
	s_waitcnt lgkmcnt(1)
	v_mfma_f32_32x32x16_bf16 v[80:95], v[112:115], v[104:107], v[80:95]
	ds_read_b128 v[112:115], v207 offset:32768
	ds_read_b128 v[120:123], v207 offset:36864
	s_waitcnt lgkmcnt(1)
	v_mfma_f32_32x32x16_bf16 v[80:95], v[112:115], v[100:103], v[80:95]
	ds_read_b128 v[116:119], v208 offset:32768
	ds_read_b128 v[112:115], v208 offset:36864
	s_waitcnt lgkmcnt(1)
	v_mfma_f32_32x32x16_bf16 v[80:95], v[116:119], v[96:99], v[80:95]
	v_exp_f32_e32 v201, v64
	v_exp_f32_e32 v199, v65
	v_exp_f32_e32 v200, v66
	v_exp_f32_e32 v198, v67
	v_exp_f32_e32 v197, v68
	v_exp_f32_e32 v195, v69
	v_exp_f32_e32 v196, v70
	v_exp_f32_e32 v194, v71
	v_exp_f32_e32 v193, v72
	v_exp_f32_e32 v191, v73
	v_exp_f32_e32 v192, v74
	v_exp_f32_e32 v190, v75
	v_exp_f32_e32 v189, v76
	v_exp_f32_e32 v187, v77
	v_exp_f32_e32 v188, v78
	v_exp_f32_e32 v186, v79
	v_cvt_pk_bf16_f32 v64, v185, v183
	v_cvt_pk_bf16_f32 v65, v184, v182
	v_cvt_pk_bf16_f32 v66, v181, v179
	v_cvt_pk_bf16_f32 v67, v180, v178
	v_cvt_pk_bf16_f32 v160, v177, v175
	v_cvt_pk_bf16_f32 v161, v176, v174
	v_cvt_pk_bf16_f32 v162, v173, v155
	v_cvt_pk_bf16_f32 v163, v172, v154
	s_nop 0
	v_permlane32_swap_b32_e32 v64, v66
	v_permlane32_swap_b32_e32 v65, v67
	v_permlane32_swap_b32_e32 v160, v162
	v_permlane32_swap_b32_e32 v161, v163
	v_cvt_pk_bf16_f32 v210, v201, v199
	v_cvt_pk_bf16_f32 v211, v200, v198
	v_cvt_pk_bf16_f32 v212, v197, v195
	v_cvt_pk_bf16_f32 v213, v196, v194
	v_cvt_pk_bf16_f32 v116, v193, v191
	v_cvt_pk_bf16_f32 v117, v192, v190
	v_cvt_pk_bf16_f32 v118, v189, v187
	v_cvt_pk_bf16_f32 v119, v188, v186
	s_nop 0
	v_permlane32_swap_b32_e32 v210, v212
	v_permlane32_swap_b32_e32 v211, v213
	v_permlane32_swap_b32_e32 v116, v118
	v_permlane32_swap_b32_e32 v117, v119
	ds_read_b64_tr_b16 v[68:69], v204 offset:0
	ds_read_b64_tr_b16 v[70:71], v204 offset:0x800
	ds_read_b64_tr_b16 v[72:73], v204 offset:0x1000
	ds_read_b64_tr_b16 v[74:75], v204 offset:0x1800
	ds_read_b64_tr_b16 v[76:77], v204 offset:0x2000
	ds_read_b64_tr_b16 v[78:79], v204 offset:0x2800
	ds_read_b64_tr_b16 v[164:165], v204 offset:0x3000
	ds_read_b64_tr_b16 v[166:167], v204 offset:0x3800
	s_waitcnt lgkmcnt(0)
	s_nop 0
	v_mfma_f32_32x32x16_bf16 v[0:15], v[64:67], v[68:71], v[0:15]
	ds_read_b64_tr_b16 v[68:69], v204 offset:0x200
	ds_read_b64_tr_b16 v[70:71], v204 offset:0xa00
	v_mfma_f32_32x32x16_bf16 v[0:15], v[160:163], v[72:75], v[0:15]
	ds_read_b64_tr_b16 v[72:73], v204 offset:0x1200
	ds_read_b64_tr_b16 v[74:75], v204 offset:0x1a00
	v_mfma_f32_32x32x16_bf16 v[0:15], v[210:213], v[76:79], v[0:15]
	ds_read_b64_tr_b16 v[76:77], v204 offset:0x2200
	ds_read_b64_tr_b16 v[78:79], v204 offset:0x2a00
	ds_read_b64_tr_b16 v[168:169], v204 offset:0x3200
	ds_read_b64_tr_b16 v[170:171], v204 offset:0x3a00
	s_waitcnt lgkmcnt(0)
	v_mfma_f32_32x32x16_bf16 v[0:15], v[116:119], v[164:167], v[0:15]
	v_mfma_f32_32x32x16_bf16 v[16:31], v[64:67], v[68:71], v[16:31]
	ds_read_b64_tr_b16 v[68:69], v204 offset:0x400
	ds_read_b64_tr_b16 v[70:71], v204 offset:0xc00
	v_mfma_f32_32x32x16_bf16 v[16:31], v[160:163], v[72:75], v[16:31]
	ds_read_b64_tr_b16 v[72:73], v204 offset:0x1400
	ds_read_b64_tr_b16 v[74:75], v204 offset:0x1c00
	v_mfma_f32_32x32x16_bf16 v[16:31], v[210:213], v[76:79], v[16:31]
	ds_read_b64_tr_b16 v[76:77], v204 offset:0x2400
	ds_read_b64_tr_b16 v[78:79], v204 offset:0x2c00
	ds_read_b64_tr_b16 v[164:165], v204 offset:0x3400
	ds_read_b64_tr_b16 v[166:167], v204 offset:0x3c00
	s_waitcnt lgkmcnt(0)
	v_mfma_f32_32x32x16_bf16 v[16:31], v[116:119], v[168:171], v[16:31]
	v_mfma_f32_32x32x16_bf16 v[32:47], v[64:67], v[68:71], v[32:47]
	ds_read_b64_tr_b16 v[68:69], v204 offset:0x600
	ds_read_b64_tr_b16 v[70:71], v204 offset:0xe00
	ds_read_b64_tr_b16 v[214:215], v204 offset:0x1600
	ds_read_b64_tr_b16 v[216:217], v204 offset:0x1e00
	ds_read_b64_tr_b16 v[224:225], v204 offset:0x2600
	ds_read_b64_tr_b16 v[226:227], v204 offset:0x2e00
	ds_read_b64_tr_b16 v[228:229], v204 offset:0x3600
	v_mfma_f32_32x32x16_bf16 v[32:47], v[160:163], v[72:75], v[32:47]
	ds_read_b64_tr_b16 v[230:231], v204 offset:0x3e00
	s_waitcnt lgkmcnt(0)
; #define SBAR() __builtin_amdgcn_sched_barrier(0)
; #define DMA_V(t, buf) do { const char* vb_ = (const char*)Vh + (size_t)(t) * TILEB; \
;         glds16(vb_ + vsrc[0], (unsigned)__builtin_amdgcn_readfirstlane(lds0 + (buf) * SHM_V + widu * 2048)); \
;         glds16(vb_ + vsrc[1], (unsigned)__builtin_amdgcn_readfirstlane(lds0 + (buf) * SHM_V + widu * 2048 + 1024)); } while (0)
; #define WBAR0() do { asm volatile("s_waitcnt vmcnt(0)" ::: "memory"); __syncthreads(); } while (0)
; #define EXPH(P) do { _Pragma("unroll") for (int r = 0; r < 16; ++r) P[r] = __builtin_amdgcn_exp2f(P[r]); } while (0)
;     ...
;         SBAR(); qkt_mix<DQK, NREG>(pA0, pA1, K_lds, qr, qs, r32, hi);
;         finishSM<true>(pB0, pB1, dummy_a, l_reg, pa0, pa1, pa2, pa3); SBAR();
;         pv_d0(o, vb0 + SHM_V, pa0, pa1, pa2, pa3);
;         if (!isY) { EXPH(pA0); }
;         WBAR0();
;     }
;     DMA_V(NT - 1, 1); SBAR();
;     if (isY) { EXPH(pA0); }
;     SBAR(); qkt_mix<DQK, NREG>(pB0, pB1, K_lds + SHM_K, qr, qs, r32, hi);
;     finishSM<true>(pA0, pA1, dummy_a, l_reg, pa0, pa1, pa2, pa3); SBAR();
;     pv_d0(o, vb0, pa0, pa1, pa2, pa3);
	v_mfma_f32_32x32x16_bf16 v[32:47], v[210:213], v[76:79], v[32:47]
	v_mfma_f32_32x32x16_bf16 v[32:47], v[116:119], v[164:167], v[32:47]
	v_mfma_f32_32x32x16_bf16 v[48:63], v[64:67], v[68:71], v[48:63]
	v_exp_f32_e32 v171, v80
	v_exp_f32_e32 v169, v81
	v_exp_f32_e32 v170, v82
	v_exp_f32_e32 v168, v83
	v_add_f32_e32 v80, v184, v200
	v_add_f32_e32 v81, v185, v201
	v_add_f32_e32 v82, v182, v198
	v_add_f32_e32 v83, v183, v199
	v_exp_f32_e32 v167, v84
	v_mfma_f32_32x32x16_bf16 v[64:79], v[156:159], v[108:111], 0
	v_exp_f32_e32 v165, v85
	v_exp_f32_e32 v166, v86
	v_exp_f32_e32 v164, v87
	v_add_f32_e32 v84, v180, v196
	v_add_f32_e32 v85, v181, v197
	v_add_f32_e32 v86, v178, v194
	v_add_f32_e32 v87, v179, v195
	v_mfma_f32_32x32x16_bf16 v[48:63], v[160:163], v[214:217], v[48:63]
	v_exp_f32_e32 v163, v88
	v_exp_f32_e32 v161, v89
	v_exp_f32_e32 v162, v90
	v_exp_f32_e32 v160, v91
	v_add_f32_e32 v88, v176, v192
	v_add_f32_e32 v89, v177, v193
	v_add_f32_e32 v90, v174, v190
	v_add_f32_e32 v91, v175, v191
	v_add_f32_e32 v80, v84, v80
	v_add_f32_e32 v81, v85, v81
	v_mfma_f32_32x32x16_bf16 v[64:79], v[124:127], v[104:107], v[64:79]
	v_add_f32_e64 v82, v86, v82
	v_add_f32_e64 v83, v87, v83
	v_exp_f32_e32 v159, v92
	v_exp_f32_e32 v157, v93
	v_exp_f32_e32 v158, v94
	v_exp_f32_e32 v156, v95
	v_add_f32_e32 v92, v172, v188
	v_add_f32_e32 v93, v173, v189
	v_add_f32_e32 v94, v154, v186
	v_add_f32_e32 v95, v155, v187
	v_mfma_f32_32x32x16_bf16 v[48:63], v[210:213], v[224:227], v[48:63]
	v_add_f32_e64 v80, v88, v80
	v_add_f32_e64 v81, v89, v81
	v_add_f32_e64 v82, v90, v82
	v_add_f32_e64 v83, v91, v83
	s_add_i32 s72, s72, 2
	v_add_f32_e32 v80, v92, v80
	v_add_f32_e32 v81, v93, v81
	v_add_f32_e32 v82, v94, v82
	v_add_f32_e32 v83, v95, v83
	s_waitcnt vmcnt(0)
	s_add_u32 s48, s48, 0xc0000
	v_mfma_f32_32x32x16_bf16 v[64:79], v[120:123], v[100:103], v[64:79]
	v_add_f32_e64 v80, v82, v80
	v_add_f32_e64 v81, v83, v81
	v_add_f32_e32 v124, v134, v141
	s_addc_u32 s49, s49, 0
	v_add_f32_e32 v80, v80, v81
	v_lshl_add_u64 v[152:153], v[152:153], 0, s[28:29]
	s_cmp_gt_u32 s72, 64
	v_add_f32_e32 v134, v124, v80
	v_mfma_f32_32x32x16_bf16 v[48:63], v[116:119], v[228:231], v[48:63]
	s_waitcnt lgkmcnt(0)
	s_barrier
	v_mfma_f32_32x32x16_bf16 v[64:79], v[112:115], v[96:99], v[64:79]
	s_cbranch_scc0 .LBB0_561
	s_cmp_lg_u32 0, -1
	s_cselect_b32 s0, 0, 0
	s_add_i32 s0, s0, s73
	v_lshl_add_u64 v[152:153], v[146:147], 0, s[38:39]
	s_add_i32 s1, s0, 0x4000
	s_mov_b32 s48, m0
	s_mov_b32 m0, s1
	s_nop 0
	global_load_lds_dwordx4 v[152:153], off
	s_mov_b32 m0, s48
	v_lshl_add_u64 v[154:155], v[146:147], 0, s[40:41]
	s_addk_i32 s0, 0x4400
	s_mov_b32 s1, m0
	s_mov_b32 m0, s0
	s_nop 0
	global_load_lds_dwordx4 v[154:155], off
	s_mov_b32 m0, s1
	ds_read_b128 v[80:83], v205 offset:40960
	ds_read_b128 v[124:127], v205 offset:45056
	ds_read_b128 v[112:115], v206 offset:40960
	ds_read_b128 v[120:123], v206 offset:45056
	s_waitcnt lgkmcnt(3)
	v_mfma_f32_32x32x16_bf16 v[80:95], v[80:83], v[108:111], 0
	s_waitcnt lgkmcnt(1)
	v_mfma_f32_32x32x16_bf16 v[80:95], v[112:115], v[104:107], v[80:95]
	ds_read_b128 v[112:115], v207 offset:40960
	ds_read_b128 v[116:119], v207 offset:45056
	s_waitcnt lgkmcnt(1)
	v_mfma_f32_32x32x16_bf16 v[80:95], v[112:115], v[100:103], v[80:95]
	ds_read_b128 v[172:175], v208 offset:40960
	ds_read_b128 v[112:115], v208 offset:45056
	s_waitcnt lgkmcnt(1)
	v_mfma_f32_32x32x16_bf16 v[80:95], v[172:175], v[96:99], v[80:95]
	v_exp_f32_e32 v173, v66
	v_exp_f32_e32 v174, v67
	v_exp_f32_e32 v177, v70
	v_exp_f32_e32 v178, v71
	v_exp_f32_e32 v181, v74
	v_exp_f32_e32 v141, v64
	v_exp_f32_e32 v182, v75
	v_add_f32_e32 v64, v170, v173
	v_exp_f32_e32 v172, v65
	v_exp_f32_e32 v185, v78
	v_add_f32_e32 v64, 0, v64
	v_add_f32_e32 v65, v168, v174
	v_add_f32_e32 v66, v166, v177
	v_exp_f32_e32 v79, v79
	v_add_f32_e32 v65, 0, v65
	v_add_f32_e32 v64, v66, v64
	v_add_f32_e32 v66, v164, v178
	v_add_f32_e32 v65, v66, v65
	v_add_f32_e32 v66, v162, v181
	v_exp_f32_e32 v175, v68
	v_exp_f32_e32 v176, v69
	v_exp_f32_e32 v179, v72
	v_exp_f32_e32 v180, v73
	v_exp_f32_e32 v183, v76
	v_exp_f32_e32 v184, v77
	v_add_f32_e32 v64, v66, v64
	v_add_f32_e32 v66, v160, v182
	v_add_f32_e32 v65, v66, v65
	v_add_f32_e32 v66, v158, v185
	v_add_f32_e32 v64, v66, v64
	v_add_f32_e32 v66, v156, v79
	v_add_f32_e32 v65, v66, v65
	v_add_f32_e32 v186, v171, v141
	v_add_f32_e32 v187, v169, v172
	v_add_f32_e32 v188, v167, v175
	v_add_f32_e32 v189, v165, v176
	v_add_f32_e32 v190, v163, v179
	v_add_f32_e32 v191, v161, v180
	v_add_f32_e32 v192, v159, v183
	v_add_f32_e32 v193, v157, v184
	v_add_f32_e32 v194, v65, v64
	v_cvt_pk_bf16_f32 v64, v171, v169
	v_cvt_pk_bf16_f32 v65, v170, v168
	v_cvt_pk_bf16_f32 v66, v167, v165
	v_cvt_pk_bf16_f32 v67, v166, v164
	v_cvt_pk_bf16_f32 v68, v163, v161
	v_cvt_pk_bf16_f32 v69, v162, v160
	v_cvt_pk_bf16_f32 v70, v159, v157
	v_cvt_pk_bf16_f32 v71, v158, v156
	s_nop 0
	v_permlane32_swap_b32_e32 v64, v66
	v_permlane32_swap_b32_e32 v65, v67
	v_permlane32_swap_b32_e32 v68, v70
	v_cvt_pk_bf16_f32 v72, v141, v172
	v_cvt_pk_bf16_f32 v73, v173, v174
	v_cvt_pk_bf16_f32 v74, v175, v176
	v_cvt_pk_bf16_f32 v75, v177, v178
	v_cvt_pk_bf16_f32 v76, v179, v180
	v_cvt_pk_bf16_f32 v77, v181, v182
	v_cvt_pk_bf16_f32 v78, v183, v184
	v_cvt_pk_bf16_f32 v79, v185, v79
	v_permlane32_swap_b32_e32 v69, v71
	v_permlane32_swap_b32_e32 v72, v74
	v_permlane32_swap_b32_e32 v73, v75
	v_permlane32_swap_b32_e32 v76, v78
	v_permlane32_swap_b32_e32 v77, v79
	ds_read_b64_tr_b16 v[156:157], v203 offset:0
	ds_read_b64_tr_b16 v[158:159], v203 offset:0x800
	ds_read_b64_tr_b16 v[160:161], v203 offset:0x1000
	ds_read_b64_tr_b16 v[162:163], v203 offset:0x1800
	ds_read_b64_tr_b16 v[164:165], v203 offset:0x2000
	ds_read_b64_tr_b16 v[166:167], v203 offset:0x2800
	ds_read_b64_tr_b16 v[168:169], v203 offset:0x3000
	ds_read_b64_tr_b16 v[170:171], v203 offset:0x3800
	s_waitcnt lgkmcnt(0)
; #define SBAR() __builtin_amdgcn_sched_barrier(0)
; #define WBAR0() do { asm volatile("s_waitcnt vmcnt(0)" ::: "memory"); __syncthreads(); } while (0)
; #define EXPH(P) do { _Pragma("unroll") for (int r = 0; r < 16; ++r) P[r] = __builtin_amdgcn_exp2f(P[r]); } while (0)
;     ...
;     pv_d0(o, vb0, pa0, pa1, pa2, pa3);
;     if (!isY) { EXPH(pB0); }
;     WBAR0();
;     if (isY) { EXPH(pB0); }
;     SBAR(); finishSM<true>(pB0, pB1, dummy_a, l_reg, pa0, pa1, pa2, pa3); SBAR();
;     pv_d0(o, vb0 + SHM_V, pa0, pa1, pa2, pa3);
	s_nop 0
	v_mfma_f32_32x32x16_bf16 v[0:15], v[64:67], v[156:159], v[0:15]
	ds_read_b64_tr_b16 v[156:157], v203 offset:0x200
	ds_read_b64_tr_b16 v[158:159], v203 offset:0xa00
	v_mfma_f32_32x32x16_bf16 v[0:15], v[68:71], v[160:163], v[0:15]
	ds_read_b64_tr_b16 v[160:161], v203 offset:0x1200
	ds_read_b64_tr_b16 v[162:163], v203 offset:0x1a00
	v_mfma_f32_32x32x16_bf16 v[0:15], v[72:75], v[164:167], v[0:15]
	ds_read_b64_tr_b16 v[164:165], v203 offset:0x2200
	ds_read_b64_tr_b16 v[166:167], v203 offset:0x2a00
	ds_read_b64_tr_b16 v[172:173], v203 offset:0x3200
	ds_read_b64_tr_b16 v[174:175], v203 offset:0x3a00
	s_waitcnt lgkmcnt(0)
	v_mfma_f32_32x32x16_bf16 v[0:15], v[76:79], v[168:171], v[0:15]
	v_mfma_f32_32x32x16_bf16 v[16:31], v[64:67], v[156:159], v[16:31]
	ds_read_b64_tr_b16 v[156:157], v203 offset:0x400
	ds_read_b64_tr_b16 v[158:159], v203 offset:0xc00
	v_mfma_f32_32x32x16_bf16 v[16:31], v[68:71], v[160:163], v[16:31]
	ds_read_b64_tr_b16 v[160:161], v203 offset:0x1400
	ds_read_b64_tr_b16 v[162:163], v203 offset:0x1c00
	v_mfma_f32_32x32x16_bf16 v[16:31], v[72:75], v[164:167], v[16:31]
	ds_read_b64_tr_b16 v[164:165], v203 offset:0x2400
	ds_read_b64_tr_b16 v[166:167], v203 offset:0x2c00
	ds_read_b64_tr_b16 v[168:169], v203 offset:0x3400
	ds_read_b64_tr_b16 v[170:171], v203 offset:0x3c00
	s_waitcnt lgkmcnt(0)
	v_mfma_f32_32x32x16_bf16 v[16:31], v[76:79], v[172:175], v[16:31]
	v_mfma_f32_32x32x16_bf16 v[32:47], v[64:67], v[156:159], v[32:47]
	ds_read_b64_tr_b16 v[156:157], v203 offset:0x600
	ds_read_b64_tr_b16 v[158:159], v203 offset:0xe00
	v_mfma_f32_32x32x16_bf16 v[32:47], v[68:71], v[160:163], v[32:47]
	ds_read_b64_tr_b16 v[160:161], v203 offset:0x1600
	ds_read_b64_tr_b16 v[162:163], v203 offset:0x1e00
	v_mfma_f32_32x32x16_bf16 v[32:47], v[72:75], v[164:167], v[32:47]
	ds_read_b64_tr_b16 v[164:165], v203 offset:0x2600
	ds_read_b64_tr_b16 v[166:167], v203 offset:0x2e00
	ds_read_b64_tr_b16 v[172:173], v203 offset:0x3600
	ds_read_b64_tr_b16 v[174:175], v203 offset:0x3e00
	s_waitcnt lgkmcnt(0)
	v_mfma_f32_32x32x16_bf16 v[32:47], v[76:79], v[168:171], v[32:47]
	v_mfma_f32_32x32x16_bf16 v[48:63], v[64:67], v[156:159], v[48:63]
	s_waitcnt vmcnt(0)
	v_exp_f32_e32 v80, v80
	v_exp_f32_e32 v81, v81
	v_exp_f32_e32 v82, v82
	v_exp_f32_e32 v83, v83
	v_exp_f32_e32 v84, v84
	v_exp_f32_e32 v85, v85
	v_mfma_f32_32x32x16_bf16 v[48:63], v[68:71], v[160:163], v[48:63]
	v_exp_f32_e32 v86, v86
	v_exp_f32_e32 v87, v87
	v_exp_f32_e32 v88, v88
	v_exp_f32_e32 v89, v89
	v_exp_f32_e32 v90, v90
	v_exp_f32_e32 v91, v91
	v_exp_f32_e32 v92, v92
	v_mfma_f32_32x32x16_bf16 v[48:63], v[72:75], v[164:167], v[48:63]
	v_exp_f32_e32 v93, v93
	v_exp_f32_e32 v94, v94
	v_exp_f32_e32 v95, v95
	s_waitcnt lgkmcnt(0)
	s_barrier
	v_mfma_f32_32x32x16_bf16 v[48:63], v[76:79], v[172:175], v[48:63]
	v_mfma_f32_32x32x16_bf16 v[64:79], v[124:127], v[108:111], 0
	v_mfma_f32_32x32x16_bf16 v[64:79], v[120:123], v[104:107], v[64:79]
	v_add_f32_e32 v104, 0, v186
	v_add_f32_e32 v105, 0, v187
	v_add_f32_e32 v104, v188, v104
	v_add_f32_e32 v105, v189, v105
	v_add_f32_e32 v104, v190, v104
	v_add_f32_e32 v105, v191, v105
	v_add_f32_e32 v104, v192, v104
	v_mfma_f32_32x32x16_bf16 v[64:79], v[116:119], v[100:103], v[64:79]
	v_add_f32_e32 v100, v193, v105
	v_add_f32_e32 v100, v100, v104
	v_add_f32_e32 v100, v194, v100
	v_add_f32_e32 v100, v134, v100
	v_mfma_f32_32x32x16_bf16 v[64:79], v[112:115], v[96:99], v[64:79]
	s_nop 11
	v_exp_f32_e32 v96, v64
	v_exp_f32_e32 v65, v65
	v_exp_f32_e32 v99, v68
	v_exp_f32_e32 v97, v66
	v_exp_f32_e32 v101, v69
	v_exp_f32_e32 v98, v67
	v_exp_f32_e32 v102, v70
	v_exp_f32_e32 v103, v71
	v_add_f32_e32 v64, v80, v96
	v_exp_f32_e32 v104, v72
	v_add_f32_e32 v64, 0, v64
	v_add_f32_e32 v66, v81, v65
	v_add_f32_e32 v69, v84, v99
	v_exp_f32_e32 v105, v73
	v_add_f32_e32 v66, 0, v66
	v_add_f32_e32 v67, v82, v97
	v_add_f32_e32 v64, v69, v64
	v_add_f32_e32 v69, v85, v101
	v_exp_f32_e32 v106, v74
	v_add_f32_e32 v67, 0, v67
	v_add_f32_e32 v68, v83, v98
	v_add_f32_e32 v66, v69, v66
	v_add_f32_e32 v69, v86, v102
	v_exp_f32_e32 v107, v75
	v_add_f32_e32 v68, 0, v68
	v_add_f32_e32 v67, v69, v67
	v_add_f32_e32 v69, v87, v103
	v_exp_f32_e32 v108, v76
	v_add_f32_e32 v68, v69, v68
	v_add_f32_e32 v69, v88, v104
	v_exp_f32_e32 v109, v77
	v_add_f32_e32 v64, v69, v64
	v_add_f32_e32 v69, v89, v105
	v_exp_f32_e32 v110, v78
	v_add_f32_e32 v66, v69, v66
	v_add_f32_e32 v69, v90, v106
	v_exp_f32_e32 v111, v79
	v_add_f32_e32 v67, v69, v67
	v_add_f32_e32 v69, v91, v107
	v_add_f32_e32 v68, v69, v68
	v_add_f32_e32 v69, v92, v108
	v_add_f32_e32 v64, v69, v64
	v_add_f32_e32 v69, v93, v109
	v_add_f32_e32 v66, v69, v66
	v_add_f32_e32 v69, v94, v110
	v_add_f32_e32 v67, v69, v67
	v_add_f32_e32 v69, v95, v111
	v_add_f32_e32 v68, v69, v68
	v_add_f32_e32 v64, v66, v64
	v_add_f32_e32 v66, v68, v67
	v_add_f32_e32 v64, v66, v64
	v_cvt_pk_bf16_f32 v66, v80, v81
	v_cvt_pk_bf16_f32 v67, v82, v83
	v_cvt_pk_bf16_f32 v68, v84, v85
	v_cvt_pk_bf16_f32 v69, v86, v87
	v_add_f32_e32 v64, v100, v64
	v_permlane32_swap_b32_e32 v66, v68
	v_permlane32_swap_b32_e32 v67, v69
	v_cvt_pk_bf16_f32 v70, v88, v89
	v_cvt_pk_bf16_f32 v71, v90, v91
	v_cvt_pk_bf16_f32 v72, v92, v93
	v_cvt_pk_bf16_f32 v73, v94, v95
	v_cvt_pk_bf16_f32 v74, v96, v65
	v_cvt_pk_bf16_f32 v75, v97, v98
	v_cvt_pk_bf16_f32 v76, v99, v101
	v_cvt_pk_bf16_f32 v77, v102, v103
	v_cvt_pk_bf16_f32 v78, v104, v105
	v_cvt_pk_bf16_f32 v79, v106, v107
	v_cvt_pk_bf16_f32 v80, v108, v109
	v_cvt_pk_bf16_f32 v81, v110, v111
	s_nop 0
	v_permlane32_swap_b32_e32 v70, v72
	v_permlane32_swap_b32_e32 v71, v73
	v_permlane32_swap_b32_e32 v74, v76
	v_permlane32_swap_b32_e32 v75, v77
	v_permlane32_swap_b32_e32 v78, v80
	v_permlane32_swap_b32_e32 v79, v81
	ds_read_b64_tr_b16 v[82:83], v204 offset:0
	ds_read_b64_tr_b16 v[84:85], v204 offset:0x800
	ds_read_b64_tr_b16 v[86:87], v204 offset:0x1000
	ds_read_b64_tr_b16 v[88:89], v204 offset:0x1800
	ds_read_b64_tr_b16 v[90:91], v204 offset:0x2000
	ds_read_b64_tr_b16 v[92:93], v204 offset:0x2800
	ds_read_b64_tr_b16 v[94:95], v204 offset:0x3000
	ds_read_b64_tr_b16 v[96:97], v204 offset:0x3800
	s_waitcnt lgkmcnt(0)
; __device__ __forceinline__ unsigned cvt_pk_bf16(float lo, float hi) { unsigned r; asm volatile("v_cvt_pk_bf16_f32 %0, %1, %2" : "=v"(r) : "v"(lo), "v"(hi)); return r; }
; __device__ __forceinline__ int crow(int r, int hi) { return (r & 3) + 8 * (r >> 2) + 4 * hi; }
;     ...
;     pv_d0(o, vb0 + SHM_V, pa0, pa1, pa2, pa3);
;     __builtin_amdgcn_s_setprio(0);
;     (void)dummy_m;
;     { auto rr = __builtin_amdgcn_permlane32_swap(__float_as_uint(l_reg), __float_as_uint(l_reg), false, false); l_reg = __uint_as_float(rr[0]) + __uint_as_float(rr[1]); }
;     {
;         int t2 = threadIdx.x; asm volatile("" : "+v"(t2));
;         const int wid2 = t2 >> 6, lane2 = t2 & 63, r32b = lane2 & 31, hib = lane2 >> 5;
;         float* li2 = (float*)(lds + OFF_WS) + wid2 * 64;
;         if (hib == 0) li2[r32b] = l_reg; asm volatile("s_waitcnt lgkmcnt(0)" ::: "memory");
;         __syncthreads();
;         bf16_t* stash = (bf16_t*)(lds + OFF_Q) + wid2 * 4096;
;         bf16_t* stg = (mode == 1) ? stash : ((bf16_t*)lds + wid2 * 4096);
; #pragma unroll
;         for (int r = 0; r < 16; ++r) { const int orow = crow(r, hib); const float rl = __builtin_amdgcn_rcpf(li2[orow]);
; #pragma unroll
;             for (int d0 = 0; d0 < 4; ++d0) { const float v = o[d0][r] * rl; stg[orow * 128 + d0 * 32 + r32b] = (bf16_t)(cvt_pk_bf16(v, v) & 0xffffu); } }
	s_nop 0
	v_mfma_f32_32x32x16_bf16 v[0:15], v[66:69], v[82:85], v[0:15]
	ds_read_b64_tr_b16 v[82:83], v204 offset:0x200
	ds_read_b64_tr_b16 v[84:85], v204 offset:0xa00
	v_mfma_f32_32x32x16_bf16 v[0:15], v[70:73], v[86:89], v[0:15]
	ds_read_b64_tr_b16 v[86:87], v204 offset:0x1200
	ds_read_b64_tr_b16 v[88:89], v204 offset:0x1a00
	v_mfma_f32_32x32x16_bf16 v[0:15], v[74:77], v[90:93], v[0:15]
	ds_read_b64_tr_b16 v[90:91], v204 offset:0x2200
	ds_read_b64_tr_b16 v[92:93], v204 offset:0x2a00
	ds_read_b64_tr_b16 v[98:99], v204 offset:0x3200
	ds_read_b64_tr_b16 v[100:101], v204 offset:0x3a00
	s_waitcnt lgkmcnt(0)
	v_mfma_f32_32x32x16_bf16 v[0:15], v[78:81], v[94:97], v[0:15]
	v_mfma_f32_32x32x16_bf16 v[16:31], v[66:69], v[82:85], v[16:31]
	ds_read_b64_tr_b16 v[82:83], v204 offset:0x400
	ds_read_b64_tr_b16 v[84:85], v204 offset:0xc00
	v_mfma_f32_32x32x16_bf16 v[16:31], v[70:73], v[86:89], v[16:31]
	ds_read_b64_tr_b16 v[86:87], v204 offset:0x1400
	ds_read_b64_tr_b16 v[88:89], v204 offset:0x1c00
	v_mfma_f32_32x32x16_bf16 v[16:31], v[74:77], v[90:93], v[16:31]
	ds_read_b64_tr_b16 v[90:91], v204 offset:0x2400
	ds_read_b64_tr_b16 v[92:93], v204 offset:0x2c00
	ds_read_b64_tr_b16 v[94:95], v204 offset:0x3400
	ds_read_b64_tr_b16 v[96:97], v204 offset:0x3c00
	s_waitcnt lgkmcnt(0)
	v_mfma_f32_32x32x16_bf16 v[16:31], v[78:81], v[98:101], v[16:31]
	v_mfma_f32_32x32x16_bf16 v[32:47], v[66:69], v[82:85], v[32:47]
	ds_read_b64_tr_b16 v[82:83], v204 offset:0x600
	ds_read_b64_tr_b16 v[84:85], v204 offset:0xe00
	v_mfma_f32_32x32x16_bf16 v[32:47], v[70:73], v[86:89], v[32:47]
	ds_read_b64_tr_b16 v[86:87], v204 offset:0x1600
	ds_read_b64_tr_b16 v[88:89], v204 offset:0x1e00
	v_mfma_f32_32x32x16_bf16 v[32:47], v[74:77], v[90:93], v[32:47]
	ds_read_b64_tr_b16 v[90:91], v204 offset:0x2600
	ds_read_b64_tr_b16 v[92:93], v204 offset:0x2e00
	ds_read_b64_tr_b16 v[98:99], v204 offset:0x3600
	ds_read_b64_tr_b16 v[100:101], v204 offset:0x3e00
	s_waitcnt lgkmcnt(0)
	v_mfma_f32_32x32x16_bf16 v[32:47], v[78:81], v[94:97], v[32:47]
	v_mfma_f32_32x32x16_bf16 v[48:63], v[66:69], v[82:85], v[48:63]
	v_mfma_f32_32x32x16_bf16 v[48:63], v[70:73], v[86:89], v[48:63]
	v_mfma_f32_32x32x16_bf16 v[48:63], v[74:77], v[90:93], v[48:63]
	v_mfma_f32_32x32x16_bf16 v[48:63], v[78:81], v[98:101], v[48:63]
	s_setprio 0
	v_mov_b32_e32 v66, v218
	v_mov_b32_e32 v68, v64
	s_nop 1
	v_permlane32_swap_b32_e32 v64, v68
	v_and_b32_e32 v69, 32, v66
	v_and_b32_e32 v67, 0x3fffffc0, v66
	v_and_b32_e32 v65, 31, v66
	v_lshl_add_u32 v67, v67, 2, s35
	v_cmp_eq_u32_e32 vcc, 0, v69
	s_and_saveexec_b64 s[0:1], vcc
	v_add_f32_e32 v64, v64, v68
	v_lshl_add_u32 v68, v65, 2, v67
	ds_write_b32 v68, v64
	s_or_b64 exec, exec, s[0:1]
	v_lshrrev_b32_e32 v64, 3, v66
	v_and_b32_e32 v64, 4, v64
	v_lshl_add_u32 v67, v64, 2, v67
	s_waitcnt lgkmcnt(0)
	s_waitcnt lgkmcnt(0)
	s_barrier
	ds_read_b32 v68, v67
	v_lshlrev_b32_e32 v66, 7, v66
	v_and_b32_e32 v66, 0xffffe000, v66
	s_add_i32 s48, 0, 0x10800
	v_add_u32_e32 v66, s48, v66
	s_waitcnt lgkmcnt(0)
	v_rcp_f32_e32 v68, v68
	v_lshlrev_b32_e32 v65, 1, v65
	v_lshlrev_b32_e32 v64, 8, v64
	v_add3_u32 v64, v66, v65, v64
	v_mul_f32_e32 v0, v0, v68
	v_cvt_pk_bf16_f32 v0, v0, v0
	ds_write_b16 v64, v0
	v_mul_f32_e32 v0, v16, v68
	v_cvt_pk_bf16_f32 v0, v0, v0
	ds_write_b16 v64, v0 offset:64
	v_mul_f32_e32 v0, v32, v68
	v_cvt_pk_bf16_f32 v0, v0, v0
	ds_write_b16 v64, v0 offset:128
	v_mul_f32_e32 v0, v48, v68
	v_cvt_pk_bf16_f32 v0, v0, v0
	ds_read_b32 v16, v67 offset:4
	ds_write_b16 v64, v0 offset:192
	v_readfirstlane_b32 s49, v202
	s_lshl_b32 s55, s49, 10
	s_cmp_lg_u32 0, -1
	s_waitcnt lgkmcnt(1)
	v_rcp_f32_e32 v16, v16
	s_cselect_b32 s0, 0, 0
	s_add_i32 s0, s0, s55
	s_add_i32 s0, s0, 0x8000
	v_mul_f32_e32 v0, v1, v16
	v_cvt_pk_bf16_f32 v0, v0, v0
	ds_write_b16 v64, v0 offset:256
	v_mul_f32_e32 v0, v17, v16
	v_cvt_pk_bf16_f32 v0, v0, v0
	ds_write_b16 v64, v0 offset:320
	v_mul_f32_e32 v0, v33, v16
	v_cvt_pk_bf16_f32 v0, v0, v0
	ds_write_b16 v64, v0 offset:384
	v_mul_f32_e32 v0, v49, v16
	v_cvt_pk_bf16_f32 v0, v0, v0
	ds_read_b32 v1, v67 offset:8
	ds_write_b16 v64, v0 offset:448
	s_waitcnt lgkmcnt(1)
	v_rcp_f32_e32 v1, v1
	s_nop 0
	v_mul_f32_e32 v0, v2, v1
	v_cvt_pk_bf16_f32 v0, v0, v0
	ds_write_b16 v64, v0 offset:512
	v_mul_f32_e32 v0, v18, v1
	v_cvt_pk_bf16_f32 v0, v0, v0
	ds_write_b16 v64, v0 offset:576
	v_mul_f32_e32 v0, v34, v1
	v_cvt_pk_bf16_f32 v0, v0, v0
	ds_write_b16 v64, v0 offset:640
	v_mul_f32_e32 v0, v50, v1
	v_cvt_pk_bf16_f32 v0, v0, v0
	ds_read_b32 v1, v67 offset:12
	ds_write_b16 v64, v0 offset:704
	s_waitcnt lgkmcnt(1)
	v_rcp_f32_e32 v1, v1
	s_nop 0
	v_mul_f32_e32 v0, v3, v1
	v_cvt_pk_bf16_f32 v0, v0, v0
	ds_write_b16 v64, v0 offset:768
	v_mul_f32_e32 v0, v19, v1
	v_cvt_pk_bf16_f32 v0, v0, v0
	ds_write_b16 v64, v0 offset:832
	v_mul_f32_e32 v0, v35, v1
	v_cvt_pk_bf16_f32 v0, v0, v0
	ds_write_b16 v64, v0 offset:896
	v_mul_f32_e32 v0, v51, v1
	v_cvt_pk_bf16_f32 v0, v0, v0
	ds_read_b32 v1, v67 offset:32
	ds_write_b16 v64, v0 offset:960
	s_waitcnt lgkmcnt(1)
	v_rcp_f32_e32 v1, v1
	s_nop 0
	v_mul_f32_e32 v0, v4, v1
	v_cvt_pk_bf16_f32 v0, v0, v0
	ds_write_b16 v64, v0 offset:2048
	v_mul_f32_e32 v0, v20, v1
	v_cvt_pk_bf16_f32 v0, v0, v0
	ds_write_b16 v64, v0 offset:2112
	v_mul_f32_e32 v0, v36, v1
	v_cvt_pk_bf16_f32 v0, v0, v0
	ds_write_b16 v64, v0 offset:2176
	v_mul_f32_e32 v0, v52, v1
	v_cvt_pk_bf16_f32 v0, v0, v0
	ds_read_b32 v1, v67 offset:36
	ds_write_b16 v64, v0 offset:2240
	s_waitcnt lgkmcnt(1)
; __device__ __forceinline__ int crow(int r, int hi) { return (r & 3) + 8 * (r >> 2) + 4 * hi; }
;     ...
;         const bf16_t* Qw = Qb + (size_t)(wid * QBLK + r32) * LDQ + hi * 8;
; #pragma unroll
;         for (int d0 = 0; d0 < NREG; ++d0) qr[d0] = *(const bf16x8*)(Qw + d0 * 16);
; #pragma unroll
;         for (int d0 = NREG; d0 < ND0; ++d0) *(bf16x8*)(qs + (d0 - NREG) * 1024) = *(const bf16x8*)(Qw + d0 * 16);
;     }
;     const int widu = __builtin_amdgcn_readfirstlane(wid);
;     const int vb0 = (int)(uintptr_t)V_lds + v_rd_base(lane);
;     unsigned ksrc[2], vsrc[2];
; #pragma unroll
;     for (int i = 0; i < 2; ++i) {
;         if (DQK == 128) { const int j = wid * 2 + i, row = 4 * j + (lane >> 4), c = (lane & 15) ^ (row & 15); ksrc[i] = (unsigned)(row * LDK + c * 8) * 2u; }
;     ...
; #pragma unroll
;         for (int r = 0; r < 16; ++r) { const int orow = crow(r, hib); const float rl = __builtin_amdgcn_rcpf(li2[orow]);
; #pragma unroll
;             for (int d0 = 0; d0 < 4; ++d0) { const float v = o[d0][r] * rl; stg[orow * 128 + d0 * 32 + r32b] = (bf16_t)(cvt_pk_bf16(v, v) & 0xffffu); } }
;         asm volatile("s_waitcnt lgkmcnt(0)" ::: "memory");
;         if (mode != 1) {
;             bf16_t* Ow = Ob + (size_t)(wid2 * QBLK) * LDO;
;             const int ch = lane2 & 15;
;             float gg[8];
;             if (mode == 2) {
; #pragma unroll
;                 for (int e = 0; e < 8; ++e) gg[e] = sg[ch * 8 + e] * 0.8f; }
; #pragma unroll
;             for (int i = 0; i < 8; ++i) { const int row = i * 4 + (lane2 >> 4); u32x4 v = *(const u32x4*)(stg + row * 128 + ch * 8);
;                 if (mode == 2) { const u32x4 v0 = *(const u32x4*)(stash + row * 128 + ch * 8); float x0[8], x1[8]; unpack8(v0, x0); unpack8(v, x1); float ss = 0.f;
; #pragma unroll
;                     for (int e = 0; e < 8; ++e) { x0[e] = x0[e] - lam * x1[e]; ss += x0[e] * x0[e]; }
;                     ss += __shfl_xor(ss, 1); ss += __shfl_xor(ss, 2); ss += __shfl_xor(ss, 4); ss += __shfl_xor(ss, 8);
;                     const float rstd = rsqrtf(ss * (1.0f / 128) + EPS);
; #pragma unroll
;                     for (int e = 0; e < 8; ++e) x0[e] = x0[e] * rstd * gg[e];
;                     v = pack8(x0); }
;                 *(u32x4*)(Ow + (size_t)row * LDO + ch * 8) = v; }
;         }
;     }
;     asm volatile("s_waitcnt vmcnt(0)" ::: "memory");
;     __syncthreads();
	v_rcp_f32_e32 v1, v1
	s_nop 0
	v_mul_f32_e32 v0, v5, v1
	v_cvt_pk_bf16_f32 v0, v0, v0
	ds_write_b16 v64, v0 offset:2304
	v_mul_f32_e32 v0, v21, v1
	v_cvt_pk_bf16_f32 v0, v0, v0
	ds_write_b16 v64, v0 offset:2368
	v_mul_f32_e32 v0, v37, v1
	v_cvt_pk_bf16_f32 v0, v0, v0
	ds_write_b16 v64, v0 offset:2432
	v_mul_f32_e32 v0, v53, v1
	v_cvt_pk_bf16_f32 v0, v0, v0
	ds_read_b32 v1, v67 offset:40
	ds_write_b16 v64, v0 offset:2496
	s_waitcnt lgkmcnt(1)
	v_rcp_f32_e32 v1, v1
	s_nop 0
	v_mul_f32_e32 v0, v6, v1
	v_cvt_pk_bf16_f32 v0, v0, v0
	ds_write_b16 v64, v0 offset:2560
	v_mul_f32_e32 v0, v22, v1
	v_cvt_pk_bf16_f32 v0, v0, v0
	ds_write_b16 v64, v0 offset:2624
	v_mul_f32_e32 v0, v38, v1
	v_cvt_pk_bf16_f32 v0, v0, v0
	ds_write_b16 v64, v0 offset:2688
	v_mul_f32_e32 v0, v54, v1
	v_cvt_pk_bf16_f32 v0, v0, v0
	ds_read_b32 v1, v67 offset:44
	ds_write_b16 v64, v0 offset:2752
	s_waitcnt lgkmcnt(1)
	v_rcp_f32_e32 v1, v1
	s_nop 0
	v_mul_f32_e32 v0, v7, v1
	v_cvt_pk_bf16_f32 v0, v0, v0
	ds_write_b16 v64, v0 offset:2816
	v_mul_f32_e32 v0, v23, v1
	v_cvt_pk_bf16_f32 v0, v0, v0
	ds_write_b16 v64, v0 offset:2880
	v_mul_f32_e32 v0, v39, v1
	v_cvt_pk_bf16_f32 v0, v0, v0
	ds_write_b16 v64, v0 offset:2944
	v_mul_f32_e32 v0, v55, v1
	v_cvt_pk_bf16_f32 v0, v0, v0
	ds_read_b32 v1, v67 offset:64
	ds_write_b16 v64, v0 offset:3008
	s_waitcnt lgkmcnt(1)
	v_rcp_f32_e32 v1, v1
	s_nop 0
	v_mul_f32_e32 v0, v8, v1
	v_cvt_pk_bf16_f32 v0, v0, v0
	ds_write_b16 v64, v0 offset:4096
	v_mul_f32_e32 v0, v24, v1
	v_cvt_pk_bf16_f32 v0, v0, v0
	ds_write_b16 v64, v0 offset:4160
	v_mul_f32_e32 v0, v40, v1
	v_cvt_pk_bf16_f32 v0, v0, v0
	ds_write_b16 v64, v0 offset:4224
	v_mul_f32_e32 v0, v56, v1
	v_cvt_pk_bf16_f32 v0, v0, v0
	ds_read_b32 v1, v67 offset:68
	ds_write_b16 v64, v0 offset:4288
	s_waitcnt lgkmcnt(1)
	v_rcp_f32_e32 v1, v1
	s_nop 0
	v_mul_f32_e32 v0, v9, v1
	v_cvt_pk_bf16_f32 v0, v0, v0
	ds_write_b16 v64, v0 offset:4352
	v_mul_f32_e32 v0, v25, v1
	v_cvt_pk_bf16_f32 v0, v0, v0
	ds_write_b16 v64, v0 offset:4416
	v_mul_f32_e32 v0, v41, v1
	v_cvt_pk_bf16_f32 v0, v0, v0
	ds_write_b16 v64, v0 offset:4480
	v_mul_f32_e32 v0, v57, v1
	v_cvt_pk_bf16_f32 v0, v0, v0
	ds_read_b32 v1, v67 offset:72
	ds_write_b16 v64, v0 offset:4544
	s_waitcnt lgkmcnt(1)
	v_rcp_f32_e32 v1, v1
	s_nop 0
	v_mul_f32_e32 v0, v10, v1
	v_cvt_pk_bf16_f32 v0, v0, v0
	ds_write_b16 v64, v0 offset:4608
	v_mul_f32_e32 v0, v26, v1
	v_cvt_pk_bf16_f32 v0, v0, v0
	ds_write_b16 v64, v0 offset:4672
	v_mul_f32_e32 v0, v42, v1
	v_cvt_pk_bf16_f32 v0, v0, v0
	ds_write_b16 v64, v0 offset:4736
	v_mul_f32_e32 v0, v58, v1
	v_cvt_pk_bf16_f32 v0, v0, v0
	ds_read_b32 v1, v67 offset:76
	ds_write_b16 v64, v0 offset:4800
	s_waitcnt lgkmcnt(1)
	v_rcp_f32_e32 v1, v1
	s_nop 0
	v_mul_f32_e32 v0, v11, v1
	v_cvt_pk_bf16_f32 v0, v0, v0
	ds_write_b16 v64, v0 offset:4864
	v_mul_f32_e32 v0, v27, v1
	v_cvt_pk_bf16_f32 v0, v0, v0
	ds_write_b16 v64, v0 offset:4928
	v_mul_f32_e32 v0, v43, v1
	v_cvt_pk_bf16_f32 v0, v0, v0
	ds_write_b16 v64, v0 offset:4992
	v_mul_f32_e32 v0, v59, v1
	v_cvt_pk_bf16_f32 v0, v0, v0
	ds_read_b32 v1, v67 offset:96
	ds_write_b16 v64, v0 offset:5056
	s_waitcnt lgkmcnt(1)
	v_rcp_f32_e32 v1, v1
	s_nop 0
	v_mul_f32_e32 v0, v12, v1
	v_cvt_pk_bf16_f32 v0, v0, v0
	ds_write_b16 v64, v0 offset:6144
	v_mul_f32_e32 v0, v28, v1
	v_cvt_pk_bf16_f32 v0, v0, v0
	ds_write_b16 v64, v0 offset:6208
	v_mul_f32_e32 v0, v44, v1
	v_cvt_pk_bf16_f32 v0, v0, v0
	ds_write_b16 v64, v0 offset:6272
	v_mul_f32_e32 v0, v60, v1
	v_cvt_pk_bf16_f32 v0, v0, v0
	ds_read_b32 v1, v67 offset:100
	ds_write_b16 v64, v0 offset:6336
	s_waitcnt lgkmcnt(1)
	v_rcp_f32_e32 v1, v1
	s_nop 0
	v_mul_f32_e32 v0, v13, v1
	v_cvt_pk_bf16_f32 v0, v0, v0
	ds_write_b16 v64, v0 offset:6400
	v_mul_f32_e32 v0, v29, v1
	v_cvt_pk_bf16_f32 v0, v0, v0
	ds_write_b16 v64, v0 offset:6464
	v_mul_f32_e32 v0, v45, v1
	v_cvt_pk_bf16_f32 v0, v0, v0
	ds_write_b16 v64, v0 offset:6528
	v_mul_f32_e32 v0, v61, v1
	v_cvt_pk_bf16_f32 v0, v0, v0
	ds_read_b32 v1, v67 offset:104
	ds_write_b16 v64, v0 offset:6592
	s_waitcnt lgkmcnt(1)
	v_rcp_f32_e32 v1, v1
	s_nop 0
	v_mul_f32_e32 v0, v14, v1
	v_cvt_pk_bf16_f32 v0, v0, v0
	ds_write_b16 v64, v0 offset:6656
	v_mul_f32_e32 v0, v30, v1
	v_cvt_pk_bf16_f32 v0, v0, v0
	ds_write_b16 v64, v0 offset:6720
	v_mul_f32_e32 v0, v46, v1
	v_cvt_pk_bf16_f32 v0, v0, v0
	ds_write_b16 v64, v0 offset:6784
	v_mul_f32_e32 v0, v62, v1
	v_cvt_pk_bf16_f32 v0, v0, v0
	ds_read_b32 v1, v67 offset:108
	ds_write_b16 v64, v0 offset:6848
	s_waitcnt lgkmcnt(1)
	v_rcp_f32_e32 v1, v1
	s_nop 0
	v_mul_f32_e32 v0, v15, v1
	v_cvt_pk_bf16_f32 v0, v0, v0
	ds_write_b16 v64, v0 offset:6912
	v_mul_f32_e32 v0, v31, v1
	v_cvt_pk_bf16_f32 v0, v0, v0
	ds_write_b16 v64, v0 offset:6976
	v_mul_f32_e32 v0, v47, v1
	v_cvt_pk_bf16_f32 v0, v0, v0
	ds_write_b16 v64, v0 offset:7040
	v_mul_f32_e32 v0, v63, v1
	v_cvt_pk_bf16_f32 v0, v0, v0
	ds_write_b16 v64, v0 offset:7104
	s_waitcnt lgkmcnt(0)
	s_waitcnt vmcnt(0)
	s_waitcnt lgkmcnt(0)
	s_barrier
	global_load_dwordx4 v[108:111], v[144:145], off offset:128 nt
	global_load_dwordx4 v[104:107], v[144:145], off offset:160 nt
	global_load_dwordx4 v[100:103], v[144:145], off offset:192 nt
	global_load_dwordx4 v[96:99], v[144:145], off offset:224 nt
	v_lshl_add_u64 v[0:1], v[150:151], 0, s[42:43]
	s_mov_b32 s1, m0
	s_mov_b32 m0, s0
	s_nop 0
	global_load_lds_dwordx4 v[0:1], off
	s_mov_b32 m0, s1
	s_waitcnt vmcnt(0)
	s_nop 0
	v_readfirstlane_b32 s1, v218
	s_cmpk_lt_i32 s1, 0x100
	s_barrier
	s_cbranch_scc1 .LBB0_566
	s_setprio 1
